# non-temporal loads also for fixup UB rows, scan chunk states and the residual-base loads of the out/down GEMM epilogues
# baseline (speedup 1.0000x reference)
; DI void hgrn_scan_phase(const Args& A, int wave_s) {
;     ...
;     for (int gid = blockIdx.x * 512 + C.tid; gid < 32 * 2048; gid += gridDim.x * 512) {
;         const int seq = gid >> 11, e = gid & 2047, k = e >> 5;
;         unsigned* SL = (unsigned*)C.ST + (size_t)seq * 132 * 2048 + e; const float* D = DEC + seq * 132 * 64 + k;
;         float s0 = 0.f, s1 = 0.f;
;         for (int n = 0; n < 132; n += 12) {
;             unsigned sl[12]; float d[12];
; #pragma unroll
;             for (int j = 0; j < 12; ++j) { sl[j] = SL[(size_t)(n + j) * 2048]; d[j] = D[(n + j) * 64]; }
.Lscan_batch:
	global_load_dword v78, v2, s[12:13] nt
	s_add_u32 s12, s12, 0x2000
	s_addc_u32 s13, s13, 0
	global_load_dword v12, v3, s[14:15] nt
	s_add_u32 s14, s14, 0x100
	s_addc_u32 s15, s15, 0
	global_load_dword v79, v2, s[12:13] nt
	s_add_u32 s12, s12, 0x2000
	s_addc_u32 s13, s13, 0
	global_load_dword v13, v3, s[14:15] nt
	s_add_u32 s14, s14, 0x100
	s_addc_u32 s15, s15, 0
	global_load_dword v80, v2, s[12:13] nt
	s_add_u32 s12, s12, 0x2000
	s_addc_u32 s13, s13, 0
	global_load_dword v14, v3, s[14:15] nt
	s_add_u32 s14, s14, 0x100
	s_addc_u32 s15, s15, 0
	global_load_dword v81, v2, s[12:13] nt
	s_add_u32 s12, s12, 0x2000
	s_addc_u32 s13, s13, 0
	global_load_dword v15, v3, s[14:15] nt
	s_add_u32 s14, s14, 0x100
	s_addc_u32 s15, s15, 0
	global_load_dword v82, v2, s[12:13] nt
	s_add_u32 s12, s12, 0x2000
	s_addc_u32 s13, s13, 0
	global_load_dword v16, v3, s[14:15] nt
	s_add_u32 s14, s14, 0x100
	s_addc_u32 s15, s15, 0
	global_load_dword v83, v2, s[12:13] nt
	s_add_u32 s12, s12, 0x2000
	s_addc_u32 s13, s13, 0
	global_load_dword v17, v3, s[14:15] nt
	s_add_u32 s14, s14, 0x100
	s_addc_u32 s15, s15, 0
	global_load_dword v84, v2, s[12:13] nt
	s_add_u32 s12, s12, 0x2000
	s_addc_u32 s13, s13, 0
	global_load_dword v18, v3, s[14:15] nt
	s_add_u32 s14, s14, 0x100
	s_addc_u32 s15, s15, 0
	global_load_dword v85, v2, s[12:13] nt
	s_add_u32 s12, s12, 0x2000
	s_addc_u32 s13, s13, 0
	global_load_dword v19, v3, s[14:15] nt
	s_add_u32 s14, s14, 0x100
	s_addc_u32 s15, s15, 0
	global_load_dword v86, v2, s[12:13] nt
	s_add_u32 s12, s12, 0x2000
	s_addc_u32 s13, s13, 0
	global_load_dword v20, v3, s[14:15] nt
	s_add_u32 s14, s14, 0x100
	s_addc_u32 s15, s15, 0
	global_load_dword v87, v2, s[12:13] nt
	s_add_u32 s12, s12, 0x2000
	s_addc_u32 s13, s13, 0
	global_load_dword v21, v3, s[14:15] nt
	s_add_u32 s14, s14, 0x100
	s_addc_u32 s15, s15, 0
	global_load_dword v88, v2, s[12:13] nt
	s_add_u32 s12, s12, 0x2000
	s_addc_u32 s13, s13, 0
	global_load_dword v22, v3, s[14:15] nt
	s_add_u32 s14, s14, 0x100
	s_addc_u32 s15, s15, 0
	global_load_dword v89, v2, s[12:13] nt
	s_add_u32 s12, s12, 0x2000
	s_addc_u32 s13, s13, 0
	global_load_dword v23, v3, s[14:15] nt
	s_add_u32 s14, s14, 0x100
	s_addc_u32 s15, s15, 0
	global_load_dword v90, v2, s[12:13] nt
	s_add_u32 s12, s12, 0x2000
	s_addc_u32 s13, s13, 0
	global_load_dword v24, v3, s[14:15] nt
	s_add_u32 s14, s14, 0x100
	s_addc_u32 s15, s15, 0
	global_load_dword v91, v2, s[12:13] nt
	s_add_u32 s12, s12, 0x2000
	s_addc_u32 s13, s13, 0
	global_load_dword v25, v3, s[14:15] nt
	s_add_u32 s14, s14, 0x100
	s_addc_u32 s15, s15, 0
	global_load_dword v92, v2, s[12:13] nt
	s_add_u32 s12, s12, 0x2000
	s_addc_u32 s13, s13, 0
	global_load_dword v26, v3, s[14:15] nt
	s_add_u32 s14, s14, 0x100
	s_addc_u32 s15, s15, 0
	global_load_dword v93, v2, s[12:13] nt
	s_add_u32 s12, s12, 0x2000
	s_addc_u32 s13, s13, 0
	global_load_dword v27, v3, s[14:15] nt
	s_add_u32 s14, s14, 0x100
	s_addc_u32 s15, s15, 0
	global_load_dword v94, v2, s[12:13] nt
	s_add_u32 s12, s12, 0x2000
	s_addc_u32 s13, s13, 0
	global_load_dword v28, v3, s[14:15] nt
	s_add_u32 s14, s14, 0x100
	s_addc_u32 s15, s15, 0
	global_load_dword v95, v2, s[12:13] nt
	s_add_u32 s12, s12, 0x2000
	s_addc_u32 s13, s13, 0
	global_load_dword v29, v3, s[14:15] nt
	s_add_u32 s14, s14, 0x100
	s_addc_u32 s15, s15, 0
	global_load_dword v96, v2, s[12:13] nt
	s_add_u32 s12, s12, 0x2000
	s_addc_u32 s13, s13, 0
	global_load_dword v30, v3, s[14:15] nt
	s_add_u32 s14, s14, 0x100
	s_addc_u32 s15, s15, 0
	global_load_dword v97, v2, s[12:13] nt
	s_add_u32 s12, s12, 0x2000
	s_addc_u32 s13, s13, 0
	global_load_dword v31, v3, s[14:15] nt
	s_add_u32 s14, s14, 0x100
	s_addc_u32 s15, s15, 0
	global_load_dword v98, v2, s[12:13] nt
	s_add_u32 s12, s12, 0x2000
	s_addc_u32 s13, s13, 0
	global_load_dword v32, v3, s[14:15] nt
	s_add_u32 s14, s14, 0x100
	s_addc_u32 s15, s15, 0
	global_load_dword v99, v2, s[12:13] nt
	s_add_u32 s12, s12, 0x2000
	s_addc_u32 s13, s13, 0
	global_load_dword v33, v3, s[14:15] nt
	s_add_u32 s14, s14, 0x100
	s_addc_u32 s15, s15, 0
	global_load_dword v100, v2, s[12:13] nt
	s_add_u32 s12, s12, 0x2000
	s_addc_u32 s13, s13, 0
	global_load_dword v34, v3, s[14:15] nt
	s_add_u32 s14, s14, 0x100
	s_addc_u32 s15, s15, 0
	global_load_dword v101, v2, s[12:13] nt
	s_add_u32 s12, s12, 0x2000
	s_addc_u32 s13, s13, 0
	global_load_dword v35, v3, s[14:15] nt
	s_add_u32 s14, s14, 0x100
	s_addc_u32 s15, s15, 0
	global_load_dword v102, v2, s[12:13] nt
	s_add_u32 s12, s12, 0x2000
	s_addc_u32 s13, s13, 0
	global_load_dword v36, v3, s[14:15] nt
	s_add_u32 s14, s14, 0x100
	s_addc_u32 s15, s15, 0
	global_load_dword v103, v2, s[12:13] nt
	s_add_u32 s12, s12, 0x2000
	s_addc_u32 s13, s13, 0
	global_load_dword v37, v3, s[14:15] nt
	s_add_u32 s14, s14, 0x100
	s_addc_u32 s15, s15, 0
	global_load_dword v104, v2, s[12:13] nt
	s_add_u32 s12, s12, 0x2000
	s_addc_u32 s13, s13, 0
	global_load_dword v38, v3, s[14:15] nt
	s_add_u32 s14, s14, 0x100
	s_addc_u32 s15, s15, 0
	global_load_dword v105, v2, s[12:13] nt
	s_add_u32 s12, s12, 0x2000
	s_addc_u32 s13, s13, 0
	global_load_dword v39, v3, s[14:15] nt
	s_add_u32 s14, s14, 0x100
	s_addc_u32 s15, s15, 0
	global_load_dword v106, v2, s[12:13] nt
	s_add_u32 s12, s12, 0x2000
	s_addc_u32 s13, s13, 0
	global_load_dword v40, v3, s[14:15] nt
	s_add_u32 s14, s14, 0x100
	s_addc_u32 s15, s15, 0
	global_load_dword v107, v2, s[12:13] nt
	s_add_u32 s12, s12, 0x2000
	s_addc_u32 s13, s13, 0
	global_load_dword v41, v3, s[14:15] nt
	s_add_u32 s14, s14, 0x100
	s_addc_u32 s15, s15, 0
	global_load_dword v108, v2, s[12:13] nt
	s_add_u32 s12, s12, 0x2000
	s_addc_u32 s13, s13, 0
	global_load_dword v42, v3, s[14:15] nt
	s_add_u32 s14, s14, 0x100
	s_addc_u32 s15, s15, 0
	global_load_dword v109, v2, s[12:13] nt
	s_add_u32 s12, s12, 0x2000
	s_addc_u32 s13, s13, 0
	global_load_dword v43, v3, s[14:15] nt
	s_add_u32 s14, s14, 0x100
	s_addc_u32 s15, s15, 0
	global_load_dword v110, v2, s[12:13] nt
	s_add_u32 s12, s12, 0x2000
	s_addc_u32 s13, s13, 0
	global_load_dword v44, v3, s[14:15] nt
	s_add_u32 s14, s14, 0x100
	s_addc_u32 s15, s15, 0
	s_sub_u32 s12, s12, 0x42000
	s_subb_u32 s13, s13, 0
	s_waitcnt vmcnt(63)
; DI unsigned pk2(float lo, float hi) { return f2bf(lo) | (f2bf(hi) << 16); }
; DI void hgrn_scan_phase(const Args& A, int wave_s) {
;     ...
;         for (int n = 0; n < 132; n += 12) {
;             unsigned sl[12]; float d[12];
; #pragma unroll
;             for (int j = 0; j < 12; ++j) { sl[j] = SL[(size_t)(n + j) * 2048]; d[j] = D[(n + j) * 64]; }
; #pragma unroll
;             for (int j = 0; j < 12; ++j) { SL[(size_t)(n + j) * 2048] = pk2(s0, s1);
;                 s0 = d[j] * s0 + __builtin_bit_cast(float, sl[j] << 16); s1 = d[j] * s1 + __builtin_bit_cast(float, sl[j] & 0xffff0000u); }
	v_bfe_u32 v8, v6, 16, 1
	v_bfe_u32 v9, v7, 16, 1
	v_add3_u32 v8, v6, v8, s79
	v_add3_u32 v9, v7, v9, s79
	v_lshrrev_b32_e32 v8, 16, v8
	v_and_or_b32 v8, v9, s82, v8
	global_store_dword v2, v8, s[12:13]
	s_add_u32 s12, s12, 0x2000
	s_addc_u32 s13, s13, 0
	v_lshlrev_b32_e32 v9, 16, v78
	v_and_b32_e32 v5, 0xffff0000, v78
	v_fma_f32 v6, v12, v6, v9
	v_fma_f32 v7, v12, v7, v5
	s_waitcnt vmcnt(63)
	v_bfe_u32 v8, v6, 16, 1
	v_bfe_u32 v9, v7, 16, 1
	v_add3_u32 v8, v6, v8, s79
	v_add3_u32 v9, v7, v9, s79
	v_lshrrev_b32_e32 v8, 16, v8
	v_and_or_b32 v8, v9, s82, v8
	global_store_dword v2, v8, s[12:13]
	s_add_u32 s12, s12, 0x2000
	s_addc_u32 s13, s13, 0
	v_lshlrev_b32_e32 v9, 16, v79
	v_and_b32_e32 v5, 0xffff0000, v79
	v_fma_f32 v6, v13, v6, v9
	v_fma_f32 v7, v13, v7, v5
	s_waitcnt vmcnt(62)
	v_bfe_u32 v8, v6, 16, 1
	v_bfe_u32 v9, v7, 16, 1
	v_add3_u32 v8, v6, v8, s79
	v_add3_u32 v9, v7, v9, s79
	v_lshrrev_b32_e32 v8, 16, v8
	v_and_or_b32 v8, v9, s82, v8
	global_store_dword v2, v8, s[12:13]
	s_add_u32 s12, s12, 0x2000
	s_addc_u32 s13, s13, 0
	v_lshlrev_b32_e32 v9, 16, v80
	v_and_b32_e32 v5, 0xffff0000, v80
	v_fma_f32 v6, v14, v6, v9
	v_fma_f32 v7, v14, v7, v5
	s_waitcnt vmcnt(61)
	v_bfe_u32 v8, v6, 16, 1
	v_bfe_u32 v9, v7, 16, 1
	v_add3_u32 v8, v6, v8, s79
	v_add3_u32 v9, v7, v9, s79
	v_lshrrev_b32_e32 v8, 16, v8
	v_and_or_b32 v8, v9, s82, v8
	global_store_dword v2, v8, s[12:13]
	s_add_u32 s12, s12, 0x2000
	s_addc_u32 s13, s13, 0
	v_lshlrev_b32_e32 v9, 16, v81
	v_and_b32_e32 v5, 0xffff0000, v81
	v_fma_f32 v6, v15, v6, v9
	v_fma_f32 v7, v15, v7, v5
	s_waitcnt vmcnt(60)
	v_bfe_u32 v8, v6, 16, 1
	v_bfe_u32 v9, v7, 16, 1
	v_add3_u32 v8, v6, v8, s79
	v_add3_u32 v9, v7, v9, s79
	v_lshrrev_b32_e32 v8, 16, v8
	v_and_or_b32 v8, v9, s82, v8
	global_store_dword v2, v8, s[12:13]
	s_add_u32 s12, s12, 0x2000
	s_addc_u32 s13, s13, 0
	v_lshlrev_b32_e32 v9, 16, v82
	v_and_b32_e32 v5, 0xffff0000, v82
	v_fma_f32 v6, v16, v6, v9
	v_fma_f32 v7, v16, v7, v5
	s_waitcnt vmcnt(59)
	v_bfe_u32 v8, v6, 16, 1
	v_bfe_u32 v9, v7, 16, 1
	v_add3_u32 v8, v6, v8, s79
	v_add3_u32 v9, v7, v9, s79
	v_lshrrev_b32_e32 v8, 16, v8
	v_and_or_b32 v8, v9, s82, v8
	global_store_dword v2, v8, s[12:13]
	s_add_u32 s12, s12, 0x2000
	s_addc_u32 s13, s13, 0
	v_lshlrev_b32_e32 v9, 16, v83
	v_and_b32_e32 v5, 0xffff0000, v83
	v_fma_f32 v6, v17, v6, v9
	v_fma_f32 v7, v17, v7, v5
	s_waitcnt vmcnt(58)
	v_bfe_u32 v8, v6, 16, 1
	v_bfe_u32 v9, v7, 16, 1
	v_add3_u32 v8, v6, v8, s79
	v_add3_u32 v9, v7, v9, s79
	v_lshrrev_b32_e32 v8, 16, v8
	v_and_or_b32 v8, v9, s82, v8
	global_store_dword v2, v8, s[12:13]
	s_add_u32 s12, s12, 0x2000
	s_addc_u32 s13, s13, 0
	v_lshlrev_b32_e32 v9, 16, v84
	v_and_b32_e32 v5, 0xffff0000, v84
	v_fma_f32 v6, v18, v6, v9
	v_fma_f32 v7, v18, v7, v5
	s_waitcnt vmcnt(57)
	v_bfe_u32 v8, v6, 16, 1
	v_bfe_u32 v9, v7, 16, 1
	v_add3_u32 v8, v6, v8, s79
	v_add3_u32 v9, v7, v9, s79
	v_lshrrev_b32_e32 v8, 16, v8
	v_and_or_b32 v8, v9, s82, v8
	global_store_dword v2, v8, s[12:13]
	s_add_u32 s12, s12, 0x2000
	s_addc_u32 s13, s13, 0
	v_lshlrev_b32_e32 v9, 16, v85
	v_and_b32_e32 v5, 0xffff0000, v85
	v_fma_f32 v6, v19, v6, v9
	v_fma_f32 v7, v19, v7, v5
	s_waitcnt vmcnt(56)
	v_bfe_u32 v8, v6, 16, 1
	v_bfe_u32 v9, v7, 16, 1
	v_add3_u32 v8, v6, v8, s79
	v_add3_u32 v9, v7, v9, s79
	v_lshrrev_b32_e32 v8, 16, v8
	v_and_or_b32 v8, v9, s82, v8
	global_store_dword v2, v8, s[12:13]
	s_add_u32 s12, s12, 0x2000
	s_addc_u32 s13, s13, 0
	v_lshlrev_b32_e32 v9, 16, v86
	v_and_b32_e32 v5, 0xffff0000, v86
	v_fma_f32 v6, v20, v6, v9
	v_fma_f32 v7, v20, v7, v5
	s_waitcnt vmcnt(55)
	v_bfe_u32 v8, v6, 16, 1
	v_bfe_u32 v9, v7, 16, 1
	v_add3_u32 v8, v6, v8, s79
	v_add3_u32 v9, v7, v9, s79
	v_lshrrev_b32_e32 v8, 16, v8
	v_and_or_b32 v8, v9, s82, v8
	global_store_dword v2, v8, s[12:13]
	s_add_u32 s12, s12, 0x2000
	s_addc_u32 s13, s13, 0
	v_lshlrev_b32_e32 v9, 16, v87
	v_and_b32_e32 v5, 0xffff0000, v87
	v_fma_f32 v6, v21, v6, v9
	v_fma_f32 v7, v21, v7, v5
	s_waitcnt vmcnt(54)
	v_bfe_u32 v8, v6, 16, 1
	v_bfe_u32 v9, v7, 16, 1
	v_add3_u32 v8, v6, v8, s79
	v_add3_u32 v9, v7, v9, s79
	v_lshrrev_b32_e32 v8, 16, v8
	v_and_or_b32 v8, v9, s82, v8
	global_store_dword v2, v8, s[12:13]
	s_add_u32 s12, s12, 0x2000
	s_addc_u32 s13, s13, 0
	v_lshlrev_b32_e32 v9, 16, v88
	v_and_b32_e32 v5, 0xffff0000, v88
	v_fma_f32 v6, v22, v6, v9
	v_fma_f32 v7, v22, v7, v5
	s_waitcnt vmcnt(53)
	v_bfe_u32 v8, v6, 16, 1
	v_bfe_u32 v9, v7, 16, 1
	v_add3_u32 v8, v6, v8, s79
	v_add3_u32 v9, v7, v9, s79
	v_lshrrev_b32_e32 v8, 16, v8
	v_and_or_b32 v8, v9, s82, v8
	global_store_dword v2, v8, s[12:13]
	s_add_u32 s12, s12, 0x2000
	s_addc_u32 s13, s13, 0
	v_lshlrev_b32_e32 v9, 16, v89
	v_and_b32_e32 v5, 0xffff0000, v89
	v_fma_f32 v6, v23, v6, v9
	v_fma_f32 v7, v23, v7, v5
	s_waitcnt vmcnt(52)
	v_bfe_u32 v8, v6, 16, 1
	v_bfe_u32 v9, v7, 16, 1
	v_add3_u32 v8, v6, v8, s79
	v_add3_u32 v9, v7, v9, s79
	v_lshrrev_b32_e32 v8, 16, v8
	v_and_or_b32 v8, v9, s82, v8
	global_store_dword v2, v8, s[12:13]
	s_add_u32 s12, s12, 0x2000
	s_addc_u32 s13, s13, 0
	v_lshlrev_b32_e32 v9, 16, v90
	v_and_b32_e32 v5, 0xffff0000, v90
	v_fma_f32 v6, v24, v6, v9
	v_fma_f32 v7, v24, v7, v5
	s_waitcnt vmcnt(51)
	v_bfe_u32 v8, v6, 16, 1
	v_bfe_u32 v9, v7, 16, 1
	v_add3_u32 v8, v6, v8, s79
	v_add3_u32 v9, v7, v9, s79
	v_lshrrev_b32_e32 v8, 16, v8
	v_and_or_b32 v8, v9, s82, v8
	global_store_dword v2, v8, s[12:13]
	s_add_u32 s12, s12, 0x2000
	s_addc_u32 s13, s13, 0
	v_lshlrev_b32_e32 v9, 16, v91
	v_and_b32_e32 v5, 0xffff0000, v91
	v_fma_f32 v6, v25, v6, v9
	v_fma_f32 v7, v25, v7, v5
	s_waitcnt vmcnt(50)
; DI unsigned pk2(float lo, float hi) { return f2bf(lo) | (f2bf(hi) << 16); }
; DI void hgrn_scan_phase(const Args& A, int wave_s) {
;     ...
; #pragma unroll
;             for (int j = 0; j < 12; ++j) { SL[(size_t)(n + j) * 2048] = pk2(s0, s1);
;                 s0 = d[j] * s0 + __builtin_bit_cast(float, sl[j] << 16); s1 = d[j] * s1 + __builtin_bit_cast(float, sl[j] & 0xffff0000u); }
	v_bfe_u32 v8, v6, 16, 1
	v_bfe_u32 v9, v7, 16, 1
	v_add3_u32 v8, v6, v8, s79
	v_add3_u32 v9, v7, v9, s79
	v_lshrrev_b32_e32 v8, 16, v8
	v_and_or_b32 v8, v9, s82, v8
	global_store_dword v2, v8, s[12:13]
	s_add_u32 s12, s12, 0x2000
	s_addc_u32 s13, s13, 0
	v_lshlrev_b32_e32 v9, 16, v92
	v_and_b32_e32 v5, 0xffff0000, v92
	v_fma_f32 v6, v26, v6, v9
	v_fma_f32 v7, v26, v7, v5
	s_waitcnt vmcnt(49)
	v_bfe_u32 v8, v6, 16, 1
	v_bfe_u32 v9, v7, 16, 1
	v_add3_u32 v8, v6, v8, s79
	v_add3_u32 v9, v7, v9, s79
	v_lshrrev_b32_e32 v8, 16, v8
	v_and_or_b32 v8, v9, s82, v8
	global_store_dword v2, v8, s[12:13]
	s_add_u32 s12, s12, 0x2000
	s_addc_u32 s13, s13, 0
	v_lshlrev_b32_e32 v9, 16, v93
	v_and_b32_e32 v5, 0xffff0000, v93
	v_fma_f32 v6, v27, v6, v9
	v_fma_f32 v7, v27, v7, v5
	s_waitcnt vmcnt(48)
	v_bfe_u32 v8, v6, 16, 1
	v_bfe_u32 v9, v7, 16, 1
	v_add3_u32 v8, v6, v8, s79
	v_add3_u32 v9, v7, v9, s79
	v_lshrrev_b32_e32 v8, 16, v8
	v_and_or_b32 v8, v9, s82, v8
	global_store_dword v2, v8, s[12:13]
	s_add_u32 s12, s12, 0x2000
	s_addc_u32 s13, s13, 0
	v_lshlrev_b32_e32 v9, 16, v94
	v_and_b32_e32 v5, 0xffff0000, v94
	v_fma_f32 v6, v28, v6, v9
	v_fma_f32 v7, v28, v7, v5
	s_waitcnt vmcnt(47)
	v_bfe_u32 v8, v6, 16, 1
	v_bfe_u32 v9, v7, 16, 1
	v_add3_u32 v8, v6, v8, s79
	v_add3_u32 v9, v7, v9, s79
	v_lshrrev_b32_e32 v8, 16, v8
	v_and_or_b32 v8, v9, s82, v8
	global_store_dword v2, v8, s[12:13]
	s_add_u32 s12, s12, 0x2000
	s_addc_u32 s13, s13, 0
	v_lshlrev_b32_e32 v9, 16, v95
	v_and_b32_e32 v5, 0xffff0000, v95
	v_fma_f32 v6, v29, v6, v9
	v_fma_f32 v7, v29, v7, v5
	s_waitcnt vmcnt(46)
	v_bfe_u32 v8, v6, 16, 1
	v_bfe_u32 v9, v7, 16, 1
	v_add3_u32 v8, v6, v8, s79
	v_add3_u32 v9, v7, v9, s79
	v_lshrrev_b32_e32 v8, 16, v8
	v_and_or_b32 v8, v9, s82, v8
	global_store_dword v2, v8, s[12:13]
	s_add_u32 s12, s12, 0x2000
	s_addc_u32 s13, s13, 0
	v_lshlrev_b32_e32 v9, 16, v96
	v_and_b32_e32 v5, 0xffff0000, v96
	v_fma_f32 v6, v30, v6, v9
	v_fma_f32 v7, v30, v7, v5
	s_waitcnt vmcnt(45)
	v_bfe_u32 v8, v6, 16, 1
	v_bfe_u32 v9, v7, 16, 1
	v_add3_u32 v8, v6, v8, s79
	v_add3_u32 v9, v7, v9, s79
	v_lshrrev_b32_e32 v8, 16, v8
	v_and_or_b32 v8, v9, s82, v8
	global_store_dword v2, v8, s[12:13]
	s_add_u32 s12, s12, 0x2000
	s_addc_u32 s13, s13, 0
	v_lshlrev_b32_e32 v9, 16, v97
	v_and_b32_e32 v5, 0xffff0000, v97
	v_fma_f32 v6, v31, v6, v9
	v_fma_f32 v7, v31, v7, v5
	s_waitcnt vmcnt(44)
	v_bfe_u32 v8, v6, 16, 1
	v_bfe_u32 v9, v7, 16, 1
	v_add3_u32 v8, v6, v8, s79
	v_add3_u32 v9, v7, v9, s79
	v_lshrrev_b32_e32 v8, 16, v8
	v_and_or_b32 v8, v9, s82, v8
	global_store_dword v2, v8, s[12:13]
	s_add_u32 s12, s12, 0x2000
	s_addc_u32 s13, s13, 0
	v_lshlrev_b32_e32 v9, 16, v98
	v_and_b32_e32 v5, 0xffff0000, v98
	v_fma_f32 v6, v32, v6, v9
	v_fma_f32 v7, v32, v7, v5
	s_waitcnt vmcnt(43)
	v_bfe_u32 v8, v6, 16, 1
	v_bfe_u32 v9, v7, 16, 1
	v_add3_u32 v8, v6, v8, s79
	v_add3_u32 v9, v7, v9, s79
	v_lshrrev_b32_e32 v8, 16, v8
	v_and_or_b32 v8, v9, s82, v8
	global_store_dword v2, v8, s[12:13]
	s_add_u32 s12, s12, 0x2000
	s_addc_u32 s13, s13, 0
	v_lshlrev_b32_e32 v9, 16, v99
	v_and_b32_e32 v5, 0xffff0000, v99
	v_fma_f32 v6, v33, v6, v9
	v_fma_f32 v7, v33, v7, v5
	s_waitcnt vmcnt(42)
	v_bfe_u32 v8, v6, 16, 1
	v_bfe_u32 v9, v7, 16, 1
	v_add3_u32 v8, v6, v8, s79
	v_add3_u32 v9, v7, v9, s79
	v_lshrrev_b32_e32 v8, 16, v8
	v_and_or_b32 v8, v9, s82, v8
	global_store_dword v2, v8, s[12:13]
	s_add_u32 s12, s12, 0x2000
	s_addc_u32 s13, s13, 0
	v_lshlrev_b32_e32 v9, 16, v100
	v_and_b32_e32 v5, 0xffff0000, v100
	v_fma_f32 v6, v34, v6, v9
	v_fma_f32 v7, v34, v7, v5
	s_waitcnt vmcnt(41)
	v_bfe_u32 v8, v6, 16, 1
	v_bfe_u32 v9, v7, 16, 1
	v_add3_u32 v8, v6, v8, s79
	v_add3_u32 v9, v7, v9, s79
	v_lshrrev_b32_e32 v8, 16, v8
	v_and_or_b32 v8, v9, s82, v8
	global_store_dword v2, v8, s[12:13]
	s_add_u32 s12, s12, 0x2000
	s_addc_u32 s13, s13, 0
	v_lshlrev_b32_e32 v9, 16, v101
	v_and_b32_e32 v5, 0xffff0000, v101
	v_fma_f32 v6, v35, v6, v9
	v_fma_f32 v7, v35, v7, v5
	s_waitcnt vmcnt(40)
; DI unsigned pk2(float lo, float hi) { return f2bf(lo) | (f2bf(hi) << 16); }
; DI void hgrn_scan_phase(const Args& A, int wave_s) {
;     ...
;     for (int gid = blockIdx.x * 512 + C.tid; gid < 32 * 2048; gid += gridDim.x * 512) {
;         const int seq = gid >> 11, e = gid & 2047, k = e >> 5;
;         unsigned* SL = (unsigned*)C.ST + (size_t)seq * 132 * 2048 + e; const float* D = DEC + seq * 132 * 64 + k;
;         float s0 = 0.f, s1 = 0.f;
;         for (int n = 0; n < 132; n += 12) {
;             unsigned sl[12]; float d[12];
; #pragma unroll
;             for (int j = 0; j < 12; ++j) { sl[j] = SL[(size_t)(n + j) * 2048]; d[j] = D[(n + j) * 64]; }
; #pragma unroll
;             for (int j = 0; j < 12; ++j) { SL[(size_t)(n + j) * 2048] = pk2(s0, s1);
;                 s0 = d[j] * s0 + __builtin_bit_cast(float, sl[j] << 16); s1 = d[j] * s1 + __builtin_bit_cast(float, sl[j] & 0xffff0000u); }
;         }
	v_bfe_u32 v8, v6, 16, 1
	v_bfe_u32 v9, v7, 16, 1
	v_add3_u32 v8, v6, v8, s79
	v_add3_u32 v9, v7, v9, s79
	v_lshrrev_b32_e32 v8, 16, v8
	v_and_or_b32 v8, v9, s82, v8
	global_store_dword v2, v8, s[12:13]
	s_add_u32 s12, s12, 0x2000
	s_addc_u32 s13, s13, 0
	v_lshlrev_b32_e32 v9, 16, v102
	v_and_b32_e32 v5, 0xffff0000, v102
	v_fma_f32 v6, v36, v6, v9
	v_fma_f32 v7, v36, v7, v5
	s_waitcnt vmcnt(39)
	v_bfe_u32 v8, v6, 16, 1
	v_bfe_u32 v9, v7, 16, 1
	v_add3_u32 v8, v6, v8, s79
	v_add3_u32 v9, v7, v9, s79
	v_lshrrev_b32_e32 v8, 16, v8
	v_and_or_b32 v8, v9, s82, v8
	global_store_dword v2, v8, s[12:13]
	s_add_u32 s12, s12, 0x2000
	s_addc_u32 s13, s13, 0
	v_lshlrev_b32_e32 v9, 16, v103
	v_and_b32_e32 v5, 0xffff0000, v103
	v_fma_f32 v6, v37, v6, v9
	v_fma_f32 v7, v37, v7, v5
	s_waitcnt vmcnt(38)
	v_bfe_u32 v8, v6, 16, 1
	v_bfe_u32 v9, v7, 16, 1
	v_add3_u32 v8, v6, v8, s79
	v_add3_u32 v9, v7, v9, s79
	v_lshrrev_b32_e32 v8, 16, v8
	v_and_or_b32 v8, v9, s82, v8
	global_store_dword v2, v8, s[12:13]
	s_add_u32 s12, s12, 0x2000
	s_addc_u32 s13, s13, 0
	v_lshlrev_b32_e32 v9, 16, v104
	v_and_b32_e32 v5, 0xffff0000, v104
	v_fma_f32 v6, v38, v6, v9
	v_fma_f32 v7, v38, v7, v5
	s_waitcnt vmcnt(37)
	v_bfe_u32 v8, v6, 16, 1
	v_bfe_u32 v9, v7, 16, 1
	v_add3_u32 v8, v6, v8, s79
	v_add3_u32 v9, v7, v9, s79
	v_lshrrev_b32_e32 v8, 16, v8
	v_and_or_b32 v8, v9, s82, v8
	global_store_dword v2, v8, s[12:13]
	s_add_u32 s12, s12, 0x2000
	s_addc_u32 s13, s13, 0
	v_lshlrev_b32_e32 v9, 16, v105
	v_and_b32_e32 v5, 0xffff0000, v105
	v_fma_f32 v6, v39, v6, v9
	v_fma_f32 v7, v39, v7, v5
	s_waitcnt vmcnt(36)
	v_bfe_u32 v8, v6, 16, 1
	v_bfe_u32 v9, v7, 16, 1
	v_add3_u32 v8, v6, v8, s79
	v_add3_u32 v9, v7, v9, s79
	v_lshrrev_b32_e32 v8, 16, v8
	v_and_or_b32 v8, v9, s82, v8
	global_store_dword v2, v8, s[12:13]
	s_add_u32 s12, s12, 0x2000
	s_addc_u32 s13, s13, 0
	v_lshlrev_b32_e32 v9, 16, v106
	v_and_b32_e32 v5, 0xffff0000, v106
	v_fma_f32 v6, v40, v6, v9
	v_fma_f32 v7, v40, v7, v5
	s_waitcnt vmcnt(35)
	v_bfe_u32 v8, v6, 16, 1
	v_bfe_u32 v9, v7, 16, 1
	v_add3_u32 v8, v6, v8, s79
	v_add3_u32 v9, v7, v9, s79
	v_lshrrev_b32_e32 v8, 16, v8
	v_and_or_b32 v8, v9, s82, v8
	global_store_dword v2, v8, s[12:13]
	s_add_u32 s12, s12, 0x2000
	s_addc_u32 s13, s13, 0
	v_lshlrev_b32_e32 v9, 16, v107
	v_and_b32_e32 v5, 0xffff0000, v107
	v_fma_f32 v6, v41, v6, v9
	v_fma_f32 v7, v41, v7, v5
	s_waitcnt vmcnt(34)
	v_bfe_u32 v8, v6, 16, 1
	v_bfe_u32 v9, v7, 16, 1
	v_add3_u32 v8, v6, v8, s79
	v_add3_u32 v9, v7, v9, s79
	v_lshrrev_b32_e32 v8, 16, v8
	v_and_or_b32 v8, v9, s82, v8
	global_store_dword v2, v8, s[12:13]
	s_add_u32 s12, s12, 0x2000
	s_addc_u32 s13, s13, 0
	v_lshlrev_b32_e32 v9, 16, v108
	v_and_b32_e32 v5, 0xffff0000, v108
	v_fma_f32 v6, v42, v6, v9
	v_fma_f32 v7, v42, v7, v5
	s_waitcnt vmcnt(33)
	v_bfe_u32 v8, v6, 16, 1
	v_bfe_u32 v9, v7, 16, 1
	v_add3_u32 v8, v6, v8, s79
	v_add3_u32 v9, v7, v9, s79
	v_lshrrev_b32_e32 v8, 16, v8
	v_and_or_b32 v8, v9, s82, v8
	global_store_dword v2, v8, s[12:13]
	s_add_u32 s12, s12, 0x2000
	s_addc_u32 s13, s13, 0
	v_lshlrev_b32_e32 v9, 16, v109
	v_and_b32_e32 v5, 0xffff0000, v109
	v_fma_f32 v6, v43, v6, v9
	v_fma_f32 v7, v43, v7, v5
	s_waitcnt vmcnt(32)
	v_bfe_u32 v8, v6, 16, 1
	v_bfe_u32 v9, v7, 16, 1
	v_add3_u32 v8, v6, v8, s79
	v_add3_u32 v9, v7, v9, s79
	v_lshrrev_b32_e32 v8, 16, v8
	v_and_or_b32 v8, v9, s82, v8
	global_store_dword v2, v8, s[12:13]
	s_add_u32 s12, s12, 0x2000
	s_addc_u32 s13, s13, 0
	v_lshlrev_b32_e32 v9, 16, v110
	v_and_b32_e32 v5, 0xffff0000, v110
	v_fma_f32 v6, v44, v6, v9
	v_fma_f32 v7, v44, v7, v5
	s_sub_u32 s16, s16, 1
	s_cmp_lg_u32 s16, 0
	s_cbranch_scc1 .Lscan_batch
	v_readlane_b32 s8, v253, 61
	s_mov_b32 s2, 0xffff
	s_nop 0
	v_add_u32_e32 v10, s8, v10
	v_cmp_lt_i32_e32 vcc, s2, v10
	s_or_b64 s[6:7], vcc, s[6:7]
	v_add_u16_e32 v11, s8, v11
	s_andn2_b64 exec, exec, s[6:7]
	s_cbranch_execnz .LBB0_301

;     __device__ __forceinline__ void operator()(const f32x4 (&acc)[2][2][4][2], const Unit& u, int wr, int wc, int fr, int fq) const {
;         const bool isctx = u.pm >= 128;
;         const int v = isctx ? 4 : (u.pm >> 5);
;         const float* bp = isctx ? base_ctx - (size_t)32768 * 1024 : base_lat;
;         float* op = isctx ? out_ctx - (size_t)32768 * 1024 : out_lat;
;         const float* g = gate + v * 6144;
;         const int row0 = u.pm * BM + wr * 64 + fr; const int col0 = u.pn * BM + wc * 32 + 4 * fq;
;         f32x4 gv[2][2];
; #pragma unroll
;         for (int bj = 0; bj < 2; ++bj)
; #pragma unroll
;             for (int n = 0; n < 2; ++n) gv[bj][n] = *(const f32x4*)(g + col0 + bj * HALF + n * 16);
; #pragma unroll
;         for (int ai = 0; ai < 2; ++ai) {
;             f32x4 bs[4][2][2];
; #pragma unroll
;             for (int m = 0; m < 4; ++m) { const size_t off = (size_t)(row0 + ai * HALF + m * 16) * 1024 + col0;
; #pragma unroll
;                 for (int bj = 0; bj < 2; ++bj)
; #pragma unroll
;                     for (int n = 0; n < 2; ++n) bs[m][bj][n] = *(const f32x4*)(bp + off + bj * HALF + n * 16); }
; #pragma unroll
;             for (int m = 0; m < 4; ++m) { const size_t off = (size_t)(row0 + ai * HALF + m * 16) * 1024 + col0;
; #pragma unroll
;                 for (int bj = 0; bj < 2; ++bj)
; #pragma unroll
;                     for (int n = 0; n < 2; ++n) *(f32x4*)(op + off + bj * HALF + n * 16) = bs[m][bj][n] + gv[bj][n] * acc[ai][bj][m][n]; }
.LBB0_472:
	s_lshr_b32 s11, s22, 5
	s_cmpk_gt_i32 s22, 0x7f
	s_mulk_i32 s11, 0x1800
	v_readlane_b32 s48, v252, 17
	s_cselect_b32 s26, 0x6000, s11
	v_readlane_b32 s62, v252, 31
	v_readlane_b32 s11, v254, 12
	v_readlane_b32 s63, v252, 32
	s_cselect_b32 s30, s11, s62
	v_readlane_b32 s11, v254, 13
	s_cselect_b32 s28, s45, s40
	s_cselect_b32 s29, s46, s39
	s_cselect_b32 s31, s11, s63
	s_ashr_i32 s27, s26, 31
	v_lshl_or_b32 v128, s24, 8, v158
	s_lshl_b64 s[26:27], s[26:27], 2
	v_ashrrev_i32_e32 v129, 31, v128
	v_lshl_add_u32 v164, s22, 8, v156
	s_add_u32 s26, s41, s26
	v_lshlrev_b64 v[150:151], 2, v[128:129]
	v_ashrrev_i32_e32 v165, 31, v164
	s_addc_u32 s27, s42, s27
	v_lshl_add_u64 v[152:153], s[28:29], 0, v[150:151]
	v_lshlrev_b64 v[154:155], 12, v[164:165]
	v_lshl_add_u64 v[128:129], s[26:27], 0, v[150:151]
	v_lshl_add_u64 v[166:167], v[152:153], 0, v[154:155]
	global_load_dwordx4 v[140:143], v[128:129], off
	global_load_dwordx4 v[136:139], v[128:129], off offset:64
	global_load_dwordx4 v[132:135], v[128:129], off offset:512
	s_nop 0
	global_load_dwordx4 v[128:131], v[128:129], off offset:576
	s_nop 0
	global_load_dwordx4 v[168:171], v[166:167], off nt
	global_load_dwordx4 v[172:175], v[166:167], off offset:64 nt
	global_load_dwordx4 v[176:179], v[166:167], off offset:512 nt
	global_load_dwordx4 v[180:183], v[166:167], off offset:576 nt
	v_or_b32_e32 v166, 16, v164
	v_or_b32_e32 v200, 32, v164
	v_ashrrev_i32_e32 v167, 31, v166
	v_ashrrev_i32_e32 v201, 31, v200
	v_lshlrev_b64 v[166:167], 12, v[166:167]
	v_lshlrev_b64 v[232:233], 12, v[200:201]
	v_or_b32_e32 v164, 48, v164
	v_lshl_add_u64 v[196:197], v[152:153], 0, v[166:167]
	v_lshl_add_u64 v[212:213], v[152:153], 0, v[232:233]
	v_ashrrev_i32_e32 v165, 31, v164
	global_load_dwordx4 v[184:187], v[196:197], off nt
	global_load_dwordx4 v[188:191], v[196:197], off offset:64 nt
	global_load_dwordx4 v[192:195], v[196:197], off offset:512 nt
	s_nop 0
	global_load_dwordx4 v[196:199], v[196:197], off offset:576 nt
	s_nop 0
	global_load_dwordx4 v[200:203], v[212:213], off nt
	global_load_dwordx4 v[204:207], v[212:213], off offset:64 nt
	global_load_dwordx4 v[208:211], v[212:213], off offset:512 nt
	s_nop 0
	global_load_dwordx4 v[212:215], v[212:213], off offset:576 nt
	v_lshlrev_b64 v[164:165], 12, v[164:165]
	v_lshl_add_u64 v[228:229], v[152:153], 0, v[164:165]
	global_load_dwordx4 v[216:219], v[228:229], off nt
	global_load_dwordx4 v[220:223], v[228:229], off offset:64 nt
	global_load_dwordx4 v[224:227], v[228:229], off offset:512 nt
	s_nop 0
	global_load_dwordx4 v[228:231], v[228:229], off offset:576 nt
	v_lshl_add_u64 v[150:151], s[30:31], 0, v[150:151]
	v_lshl_add_u64 v[234:235], v[150:151], 0, v[154:155]
	s_mov_b64 s[26:27], 0x80000
	v_lshl_add_u64 v[166:167], v[150:151], 0, v[166:167]
	v_lshl_add_u64 v[232:233], v[150:151], 0, v[232:233]
	v_readlane_b32 s49, v252, 18
	v_readlane_b32 s50, v252, 19
	v_readlane_b32 s51, v252, 20
	v_readlane_b32 s52, v252, 21
	v_readlane_b32 s53, v252, 22
	v_readlane_b32 s54, v252, 23
	v_readlane_b32 s55, v252, 24
	v_readlane_b32 s56, v252, 25
	v_readlane_b32 s57, v252, 26
	v_readlane_b32 s58, v252, 27
	v_readlane_b32 s59, v252, 28
	v_readlane_b32 s60, v252, 29
	v_readlane_b32 s61, v252, 30
	v_readlane_b32 s34, v255, 19
	s_andn2_b64 vcc, exec, s[4:5]
	s_mov_b64 s[4:5], -1
	v_readlane_b32 s48, v252, 1
	v_readlane_b32 s35, v255, 20
	v_readlane_b32 s49, v252, 2
	v_readlane_b32 s50, v252, 3
	v_readlane_b32 s51, v252, 4
	v_readlane_b32 s52, v252, 5
	v_readlane_b32 s53, v252, 6
	v_readlane_b32 s54, v252, 7
	v_readlane_b32 s55, v252, 8
	v_readlane_b32 s56, v252, 9
	v_readlane_b32 s57, v252, 10
	v_readlane_b32 s58, v252, 11
	v_readlane_b32 s59, v252, 12
	v_readlane_b32 s60, v252, 13
	v_readlane_b32 s61, v252, 14
	v_readlane_b32 s62, v252, 15
	v_readlane_b32 s63, v252, 16
	s_waitcnt vmcnt(0)
	v_pk_fma_f32 v[126:127], v[126:127], v[142:143], v[170:171]
	v_pk_fma_f32 v[124:125], v[124:125], v[140:141], v[168:169]
	v_pk_fma_f32 v[122:123], v[122:123], v[138:139], v[174:175]
	v_pk_fma_f32 v[120:121], v[120:121], v[136:137], v[172:173]
	v_pk_fma_f32 v[106:107], v[106:107], v[134:135], v[178:179]
	v_pk_fma_f32 v[104:105], v[104:105], v[132:133], v[176:177]
	v_pk_fma_f32 v[102:103], v[102:103], v[130:131], v[182:183]
	v_pk_fma_f32 v[100:101], v[100:101], v[128:129], v[180:181]
	v_pk_fma_f32 v[118:119], v[118:119], v[142:143], v[186:187]
	v_pk_fma_f32 v[116:117], v[116:117], v[140:141], v[184:185]
	v_pk_fma_f32 v[114:115], v[114:115], v[138:139], v[190:191]
	v_pk_fma_f32 v[84:85], v[84:85], v[132:133], v[208:209]
	v_pk_fma_f32 v[112:113], v[112:113], v[136:137], v[188:189]
	v_pk_fma_f32 v[94:95], v[94:95], v[134:135], v[194:195]
	v_pk_fma_f32 v[92:93], v[92:93], v[132:133], v[192:193]
	v_pk_fma_f32 v[90:91], v[90:91], v[130:131], v[198:199]
	v_pk_fma_f32 v[88:89], v[88:89], v[128:129], v[196:197]
	v_pk_fma_f32 v[110:111], v[110:111], v[142:143], v[202:203]
	v_pk_fma_f32 v[108:109], v[108:109], v[140:141], v[200:201]
	v_pk_fma_f32 v[98:99], v[98:99], v[138:139], v[206:207]
	v_pk_fma_f32 v[96:97], v[96:97], v[136:137], v[204:205]
	v_pk_fma_f32 v[86:87], v[86:87], v[134:135], v[210:211]
	global_store_dwordx4 v[234:235], v[124:127], off
	global_store_dwordx4 v[234:235], v[120:123], off offset:64
	global_store_dwordx4 v[234:235], v[104:107], off offset:512
	global_store_dwordx4 v[234:235], v[100:103], off offset:576
	global_store_dwordx4 v[166:167], v[116:119], off
	global_store_dwordx4 v[166:167], v[112:115], off offset:64
	global_store_dwordx4 v[166:167], v[92:95], off offset:512
	global_store_dwordx4 v[166:167], v[88:91], off offset:576
	global_store_dwordx4 v[232:233], v[108:111], off
;     __device__ __forceinline__ void operator()(const f32x4 (&acc)[2][2][4][2], const Unit& u, int wr, int wc, int fr, int fq) const {
;     ...
; #pragma unroll
;         for (int ai = 0; ai < 2; ++ai) {
;             f32x4 bs[4][2][2];
; #pragma unroll
;             for (int m = 0; m < 4; ++m) { const size_t off = (size_t)(row0 + ai * HALF + m * 16) * 1024 + col0;
; #pragma unroll
;                 for (int bj = 0; bj < 2; ++bj)
; #pragma unroll
;                     for (int n = 0; n < 2; ++n) bs[m][bj][n] = *(const f32x4*)(bp + off + bj * HALF + n * 16); }
; #pragma unroll
;             for (int m = 0; m < 4; ++m) { const size_t off = (size_t)(row0 + ai * HALF + m * 16) * 1024 + col0;
; #pragma unroll
;                 for (int bj = 0; bj < 2; ++bj)
; #pragma unroll
;                     for (int n = 0; n < 2; ++n) *(f32x4*)(op + off + bj * HALF + n * 16) = bs[m][bj][n] + gv[bj][n] * acc[ai][bj][m][n]; }
;             asm volatile("" ::: "memory");
;         }
	global_store_dwordx4 v[232:233], v[96:99], off offset:64
	global_store_dwordx4 v[232:233], v[84:87], off offset:512
	v_pk_fma_f32 v[74:75], v[74:75], v[130:131], v[214:215]
	v_pk_fma_f32 v[72:73], v[72:73], v[128:129], v[212:213]
	v_lshl_add_u64 v[84:85], v[150:151], 0, v[164:165]
	v_lshl_add_u64 v[164:165], v[154:155], 0, s[26:27]
	s_mov_b64 s[26:27], 0x90000
	global_store_dwordx4 v[232:233], v[72:75], off offset:576
	v_lshl_add_u64 v[166:167], v[154:155], 0, s[26:27]
	s_mov_b64 s[26:27], 0xa0000
	v_pk_fma_f32 v[74:75], v[82:83], v[142:143], v[218:219]
	v_pk_fma_f32 v[72:73], v[80:81], v[140:141], v[216:217]
	global_store_dwordx4 v[84:85], v[72:75], off
	v_pk_fma_f32 v[70:71], v[70:71], v[134:135], v[226:227]
	v_pk_fma_f32 v[68:69], v[68:69], v[132:133], v[224:225]
	v_pk_fma_f32 v[74:75], v[78:79], v[138:139], v[222:223]
	v_pk_fma_f32 v[72:73], v[76:77], v[136:137], v[220:221]
	v_pk_fma_f32 v[66:67], v[66:67], v[130:131], v[230:231]
	v_pk_fma_f32 v[64:65], v[64:65], v[128:129], v[228:229]
	v_lshl_add_u64 v[168:169], v[154:155], 0, s[26:27]
	s_mov_b64 s[26:27], 0xb0000
	global_store_dwordx4 v[84:85], v[72:75], off offset:64
	global_store_dwordx4 v[84:85], v[68:71], off offset:512
	global_store_dwordx4 v[84:85], v[64:67], off offset:576
	v_lshl_add_u64 v[154:155], v[154:155], 0, s[26:27]
	v_lshl_add_u64 v[76:77], v[152:153], 0, v[164:165]
	v_lshl_add_u64 v[92:93], v[152:153], 0, v[166:167]
	v_lshl_add_u64 v[108:109], v[152:153], 0, v[168:169]
	v_lshl_add_u64 v[124:125], v[152:153], 0, v[154:155]
	global_load_dwordx4 v[64:67], v[76:77], off nt
	global_load_dwordx4 v[68:71], v[76:77], off offset:64 nt
	global_load_dwordx4 v[72:75], v[76:77], off offset:512 nt
	s_nop 0
	global_load_dwordx4 v[76:79], v[76:77], off offset:576 nt
	s_nop 0
	global_load_dwordx4 v[80:83], v[92:93], off nt
	global_load_dwordx4 v[84:87], v[92:93], off offset:64 nt
	global_load_dwordx4 v[88:91], v[92:93], off offset:512 nt
	s_nop 0
	global_load_dwordx4 v[92:95], v[92:93], off offset:576 nt
	s_nop 0
	global_load_dwordx4 v[96:99], v[108:109], off nt
	global_load_dwordx4 v[100:103], v[108:109], off offset:64 nt
	global_load_dwordx4 v[104:107], v[108:109], off offset:512 nt
	s_nop 0
	global_load_dwordx4 v[108:111], v[108:109], off offset:576 nt
	s_nop 0
	global_load_dwordx4 v[112:115], v[124:125], off nt
	global_load_dwordx4 v[116:119], v[124:125], off offset:64 nt
	global_load_dwordx4 v[120:123], v[124:125], off offset:512 nt
	s_nop 0
	global_load_dwordx4 v[124:127], v[124:125], off offset:576 nt
	v_lshl_add_u64 v[152:153], v[150:151], 0, v[164:165]
	v_lshl_add_u64 v[164:165], v[150:151], 0, v[166:167]
	v_lshl_add_u64 v[166:167], v[150:151], 0, v[168:169]
	v_lshl_add_u64 v[150:151], v[150:151], 0, v[154:155]
	s_waitcnt vmcnt(15)
	v_pk_fma_f32 v[62:63], v[62:63], v[142:143], v[66:67]
	v_pk_fma_f32 v[60:61], v[60:61], v[140:141], v[64:65]
	s_waitcnt vmcnt(14)
	v_pk_fma_f32 v[58:59], v[58:59], v[138:139], v[70:71]
	v_pk_fma_f32 v[56:57], v[56:57], v[136:137], v[68:69]
	s_waitcnt vmcnt(2)
	v_pk_fma_f32 v[10:11], v[10:11], v[138:139], v[118:119]
	v_pk_fma_f32 v[8:9], v[8:9], v[136:137], v[116:117]
	s_waitcnt vmcnt(1)
	v_pk_fma_f32 v[6:7], v[6:7], v[134:135], v[122:123]
	v_pk_fma_f32 v[4:5], v[4:5], v[132:133], v[120:121]
	s_waitcnt vmcnt(0)
	v_pk_fma_f32 v[2:3], v[2:3], v[130:131], v[126:127]
	v_pk_fma_f32 v[0:1], v[0:1], v[128:129], v[124:125]
	v_pk_fma_f32 v[42:43], v[42:43], v[134:135], v[74:75]
	v_pk_fma_f32 v[40:41], v[40:41], v[132:133], v[72:73]
	v_pk_fma_f32 v[34:35], v[34:35], v[130:131], v[78:79]
	v_pk_fma_f32 v[32:33], v[32:33], v[128:129], v[76:77]
	v_pk_fma_f32 v[54:55], v[54:55], v[142:143], v[82:83]
	v_pk_fma_f32 v[52:53], v[52:53], v[140:141], v[80:81]
	v_pk_fma_f32 v[50:51], v[50:51], v[138:139], v[86:87]
	v_pk_fma_f32 v[48:49], v[48:49], v[136:137], v[84:85]
	v_pk_fma_f32 v[26:27], v[26:27], v[134:135], v[90:91]
	v_pk_fma_f32 v[24:25], v[24:25], v[132:133], v[88:89]
	v_pk_fma_f32 v[22:23], v[22:23], v[130:131], v[94:95]
	v_pk_fma_f32 v[20:21], v[20:21], v[128:129], v[92:93]
	v_pk_fma_f32 v[46:47], v[46:47], v[142:143], v[98:99]
	v_pk_fma_f32 v[44:45], v[44:45], v[140:141], v[96:97]
	v_pk_fma_f32 v[38:39], v[38:39], v[138:139], v[102:103]
	v_pk_fma_f32 v[36:37], v[36:37], v[136:137], v[100:101]
	v_pk_fma_f32 v[18:19], v[18:19], v[134:135], v[106:107]
	v_pk_fma_f32 v[16:17], v[16:17], v[132:133], v[104:105]
	v_pk_fma_f32 v[14:15], v[14:15], v[130:131], v[110:111]
	v_pk_fma_f32 v[12:13], v[12:13], v[128:129], v[108:109]
	v_pk_fma_f32 v[30:31], v[30:31], v[142:143], v[114:115]
	v_pk_fma_f32 v[28:29], v[28:29], v[140:141], v[112:113]
	global_store_dwordx4 v[152:153], v[60:63], off
	global_store_dwordx4 v[152:153], v[56:59], off offset:64
	global_store_dwordx4 v[152:153], v[40:43], off offset:512
	global_store_dwordx4 v[152:153], v[32:35], off offset:576
	global_store_dwordx4 v[164:165], v[52:55], off
	global_store_dwordx4 v[164:165], v[48:51], off offset:64
	global_store_dwordx4 v[164:165], v[24:27], off offset:512
	global_store_dwordx4 v[164:165], v[20:23], off offset:576
	global_store_dwordx4 v[166:167], v[44:47], off
	global_store_dwordx4 v[166:167], v[36:39], off offset:64
	global_store_dwordx4 v[166:167], v[16:19], off offset:512
	global_store_dwordx4 v[166:167], v[12:15], off offset:576
	global_store_dwordx4 v[150:151], v[28:31], off
	global_store_dwordx4 v[150:151], v[8:11], off offset:64
	global_store_dwordx4 v[150:151], v[4:7], off offset:512
	global_store_dwordx4 v[150:151], v[0:3], off offset:576
	s_cbranch_vccnz .LBB0_465
	s_andn2_b64 vcc, exec, s[6:7]
	s_cbranch_vccnz .LBB0_464
	s_barrier
	s_branch .LBB0_464

; DI void ffn_fixup_phase(const Args& A, int wave_s, int l, int rows) {
;     ...
;     for (int e = blockIdx.x * 512 + C.tid; e < total; e += gridDim.x * 512) {
;         const int c8 = (e % 352) * 8, rs = e / 352, side = rs & 1, kb = rs >> 1;
;         const int R = kb * 64 + (side ? 63 : 0);
;         bool first, last;
;         if (R < NLAT) { first = (R & 8191) == 0; last = (R & 8191) == 8191; } else { first = ((R - NLAT) & 255) == 0; last = ((R - NLAT) & 255) == 255; }
;         const v4u z = {0u, 0u, 0u, 0u};
;         const bf16* pp = side ? UB + (size_t)((kb * 4 + 2) * 2) * 2816 : UB + (size_t)(((kb - 1) * 4 + 3) * 2) * 2816;
;         const bf16* pc = UB + (size_t)((kb * 4 + (side ? 3 : 0)) * 2) * 2816;
;         const bf16* pn = side ? UB + (size_t)(((kb + 1) * 4 + 0) * 2) * 2816 : UB + (size_t)((kb * 4 + 1) * 2) * 2816;
;         const bool zp = (!side) && first, zn = side && last;
;         const v4u a0 = zp ? z : *(const v4u*)(pp + c8), a1 = *(const v4u*)(pc + c8), a2 = zn ? z : *(const v4u*)(pn + c8);
;         const v4u b0 = zp ? z : *(const v4u*)(pp + 2816 + c8), b1 = *(const v4u*)(pc + 2816 + c8), b2 = zn ? z : *(const v4u*)(pn + 2816 + c8);
.LBB0_696:
	s_or_b64 exec, exec, s[4:5]
	s_lshr_b32 s2, s42, 5
	v_readlane_b32 s4, v253, 37
	s_waitcnt lgkmcnt(0)
	s_barrier
	v_mbcnt_lo_u32_b32 v0, -1, 0
	v_mbcnt_hi_u32_b32 v0, -1, v0
	v_mbcnt_lo_u32_b32 v0, -1, 0
	v_mbcnt_hi_u32_b32 v0, -1, v0
	v_readlane_b32 s6, v255, 32
	s_lshr_b32 s5, s94, 6
	s_lshl_b32 s7, s65, 3
	s_add_u32 s5, s5, s7
	s_cmp_ge_u32 s5, 2046
	s_cbranch_scc1 .Lfix_f_done
	s_lshr_b32 s6, s6, 10
	s_lshl_b32 s7, s5, 6
	v_add_u32_e32 v224, s7, v0
	v_mov_b32_e32 v225, 0xba2e8c
	v_mul_hi_u32 v225, v224, v225
	v_mov_b32_e32 v226, 0x160
	v_mul_lo_u32 v226, v225, v226
	v_sub_u32_e32 v226, v224, v226
	v_lshlrev_b32_e32 v227, 4, v226
	v_readlane_b32 s8, v252, 25
	v_readlane_b32 s9, v252, 26
	v_readlane_b32 s24, v252, 27
	v_readlane_b32 s25, v252, 28
	s_mul_i32 s7, s6, 0x10800
	s_nop 0
	s_add_u32 s8, s8, s7
	s_addc_u32 s9, s9, 0
	s_mul_i32 s7, s6, 0x5800
	s_add_u32 s24, s24, s7
	s_addc_u32 s25, s25, 0
	v_lshlrev_b32_e32 v228, 5, v226
	s_add_u32 s26, s8, 0x0
	s_addc_u32 s27, s9, 0
	global_load_dwordx4 v[4:7], v228, s[26:27]
	global_load_dwordx4 v[8:11], v228, s[26:27] offset:16
	s_add_u32 s26, s8, 0x5800
	s_addc_u32 s27, s9, 0
	global_load_dwordx4 v[12:15], v228, s[26:27]
	global_load_dwordx4 v[24:27], v228, s[26:27] offset:16
	s_add_u32 s26, s8, 0xb000
	s_addc_u32 s27, s9, 0
	global_load_dwordx4 v[28:31], v228, s[26:27]
	global_load_dwordx4 v[32:35], v228, s[26:27] offset:16
	s_add_u32 s26, s8, 0x2c00
	s_addc_u32 s27, s9, 0
	global_load_dwordx4 v[64:67], v228, s[26:27]
	global_load_dwordx4 v[68:71], v228, s[26:27] offset:16
	s_add_u32 s26, s8, 0x8400
	s_addc_u32 s27, s9, 0
	global_load_dwordx4 v[72:75], v228, s[26:27]
	global_load_dwordx4 v[80:83], v228, s[26:27] offset:16
	s_add_u32 s26, s8, 0xdc00
	s_addc_u32 s27, s9, 0
	global_load_dwordx4 v[84:87], v228, s[26:27]
	global_load_dwordx4 v[88:91], v228, s[26:27] offset:16
	s_add_u32 s26, s24, 0x0
	s_addc_u32 s27, s25, 0
	global_load_dwordx4 v[36:39], v228, s[26:27]
	global_load_dwordx4 v[40:43], v228, s[26:27] offset:16
	s_add_u32 s26, s24, 0x2c00
	s_addc_u32 s27, s25, 0
	global_load_dwordx4 v[92:95], v228, s[26:27]
	global_load_dwordx4 v[96:99], v228, s[26:27] offset:16
	s_add_u32 s28, s88, 0x171fd400
	s_addc_u32 s29, s89, 0
	s_add_u32 s30, s88, 0xbc00000
	s_addc_u32 s31, s89, 0
	v_mov_b32_e32 v229, v225
	v_and_b32_e32 v184, 1, v229
	v_lshrrev_b32_e32 v185, 1, v229
	v_lshlrev_b32_e32 v185, 2, v185
	v_mad_u32_u24 v185, v184, 3, v185
	v_mov_b32_e32 v184, 0x2c00
	v_mul_lo_u32 v185, v185, v184
	v_add_u32_e32 v185, v185, v227
	v_mov_b32_e32 v177, 0
	v_mov_b32_e32 v176, v185
	v_lshl_add_u64 v[176:177], v[176:177], 0, s[28:29]
	global_load_dwordx4 v[100:103], v[176:177], off nt
	s_mov_b64 s[26:27], 5632
	v_lshl_add_u64 v[178:179], v[176:177], 0, s[26:27]
	global_load_dwordx4 v[104:107], v[178:179], off nt
	s_mov_b64 s[26:27], 11264
	v_lshl_add_u64 v[178:179], v[176:177], 0, s[26:27]
	global_load_dwordx4 v[108:111], v[178:179], off nt
	s_mov_b64 s[26:27], 16896
	v_lshl_add_u64 v[178:179], v[176:177], 0, s[26:27]
	global_load_dwordx4 v[112:115], v[178:179], off nt
	s_mov_b64 s[26:27], 22528
	v_lshl_add_u64 v[178:179], v[176:177], 0, s[26:27]
	global_load_dwordx4 v[116:119], v[178:179], off nt
	s_mov_b64 s[26:27], 28160
	v_lshl_add_u64 v[178:179], v[176:177], 0, s[26:27]
	global_load_dwordx4 v[120:123], v[178:179], off nt
	v_add_u32_e32 v230, 372, v225
	v_and_b32_e32 v184, 1, v230
	v_lshrrev_b32_e32 v185, 1, v230
	v_lshlrev_b32_e32 v185, 2, v185
	v_mad_u32_u24 v185, v184, 3, v185
	v_mov_b32_e32 v184, 0x2c00
	v_mul_lo_u32 v185, v185, v184
	v_add_u32_e32 v185, v185, v227
	v_mov_b32_e32 v177, 0
	v_mov_b32_e32 v176, v185
	v_lshl_add_u64 v[176:177], v[176:177], 0, s[28:29]
	global_load_dwordx4 v[124:127], v[176:177], off nt
	s_mov_b64 s[26:27], 5632
	v_lshl_add_u64 v[178:179], v[176:177], 0, s[26:27]
	global_load_dwordx4 v[128:131], v[178:179], off nt
	s_mov_b64 s[26:27], 11264
	v_lshl_add_u64 v[178:179], v[176:177], 0, s[26:27]
	global_load_dwordx4 v[132:135], v[178:179], off nt
	s_mov_b64 s[26:27], 16896
	v_lshl_add_u64 v[178:179], v[176:177], 0, s[26:27]
	global_load_dwordx4 v[136:139], v[178:179], off nt
	s_mov_b64 s[26:27], 22528
	v_lshl_add_u64 v[178:179], v[176:177], 0, s[26:27]
	global_load_dwordx4 v[140:143], v[178:179], off nt
	s_mov_b64 s[26:27], 28160
	v_lshl_add_u64 v[178:179], v[176:177], 0, s[26:27]
	global_load_dwordx4 v[144:147], v[178:179], off nt
	v_add_u32_e32 v231, 744, v225
	v_and_b32_e32 v184, 1, v231
	v_lshrrev_b32_e32 v185, 1, v231
	v_lshlrev_b32_e32 v185, 2, v185
	v_mad_u32_u24 v185, v184, 3, v185
	v_mov_b32_e32 v184, 0x2c00
	v_mul_lo_u32 v185, v185, v184
	v_add_u32_e32 v185, v185, v227
	v_mov_b32_e32 v177, 0
	v_mov_b32_e32 v176, v185
	v_lshl_add_u64 v[176:177], v[176:177], 0, s[28:29]
	global_load_dwordx4 v[148:151], v[176:177], off nt
	s_mov_b64 s[26:27], 5632
	v_lshl_add_u64 v[178:179], v[176:177], 0, s[26:27]
	global_load_dwordx4 v[152:155], v[178:179], off nt
	s_mov_b64 s[26:27], 11264
	v_lshl_add_u64 v[178:179], v[176:177], 0, s[26:27]
	global_load_dwordx4 v[156:159], v[178:179], off nt
	s_mov_b64 s[26:27], 16896
	v_lshl_add_u64 v[178:179], v[176:177], 0, s[26:27]
	global_load_dwordx4 v[164:167], v[178:179], off nt
	s_mov_b64 s[26:27], 22528
	v_lshl_add_u64 v[178:179], v[176:177], 0, s[26:27]
	global_load_dwordx4 v[168:171], v[178:179], off nt
	s_mov_b64 s[26:27], 28160
	v_lshl_add_u64 v[178:179], v[176:177], 0, s[26:27]
	global_load_dwordx4 v[172:175], v[178:179], off nt
	s_mul_i32 s7, s42, 11
	s_mov_b32 s10, 0x7fff
	s_mov_b32 s11, 0xffff0000
	s_waitcnt vmcnt(12)
; DI float silu_f(float x) { return x / (1.f + __expf(-x)); }
; DI void ffn_fixup_phase(const Args& A, int wave_s, int l, int rows) {
;     ...
;         const int R = kb * 64 + (side ? 63 : 0);
;         bool first, last;
;         if (R < NLAT) { first = (R & 8191) == 0; last = (R & 8191) == 8191; } else { first = ((R - NLAT) & 255) == 0; last = ((R - NLAT) & 255) == 255; }
;         const v4u z = {0u, 0u, 0u, 0u};
;         const bf16* pp = side ? UB + (size_t)((kb * 4 + 2) * 2) * 2816 : UB + (size_t)(((kb - 1) * 4 + 3) * 2) * 2816;
;         const bf16* pc = UB + (size_t)((kb * 4 + (side ? 3 : 0)) * 2) * 2816;
;         const bf16* pn = side ? UB + (size_t)(((kb + 1) * 4 + 0) * 2) * 2816 : UB + (size_t)((kb * 4 + 1) * 2) * 2816;
;         const bool zp = (!side) && first, zn = side && last;
;         const v4u a0 = zp ? z : *(const v4u*)(pp + c8), a1 = *(const v4u*)(pc + c8), a2 = zn ? z : *(const v4u*)(pn + c8);
;         const v4u b0 = zp ? z : *(const v4u*)(pp + 2816 + c8), b1 = *(const v4u*)(pc + 2816 + c8), b2 = zn ? z : *(const v4u*)(pn + 2816 + c8);
;         unsigned res[4];
; #pragma unroll
;         for (int q = 0; q < 4; ++q) {
;             float r2[2];
; #pragma unroll
;             for (int hlf = 0; hlf < 2; ++hlf) {
;                 const int i = c8 + 2 * q + hlf;
;                 const float ua0 = hlf ? __builtin_bit_cast(float, a0[q] & 0xffff0000u) : __builtin_bit_cast(float, a0[q] << 16);
;                 const float ua1 = hlf ? __builtin_bit_cast(float, a1[q] & 0xffff0000u) : __builtin_bit_cast(float, a1[q] << 16);
;                 const float ua2 = hlf ? __builtin_bit_cast(float, a2[q] & 0xffff0000u) : __builtin_bit_cast(float, a2[q] << 16);
;                 const float ub0 = hlf ? __builtin_bit_cast(float, b0[q] & 0xffff0000u) : __builtin_bit_cast(float, b0[q] << 16);
;                 const float ub1 = hlf ? __builtin_bit_cast(float, b1[q] & 0xffff0000u) : __builtin_bit_cast(float, b1[q] << 16);
;                 const float ub2 = hlf ? __builtin_bit_cast(float, b2[q] & 0xffff0000u) : __builtin_bit_cast(float, b2[q] << 16);
;                 const float ya = cb[i] + ua0 * cw[i] + ua1 * cw[5632 + i] + ua2 * cw[2 * 5632 + i];
;                 const float yv = cb[2816 + i] + ub0 * cw[2816 + i] + ub1 * cw[5632 + 2816 + i] + ub2 * cw[2 * 5632 + 2816 + i];
;                 r2[hlf] = silu_f(ya) * yv;
	v_and_b32_e32 v188, 1, v229
	v_lshrrev_b32_e32 v190, 1, v229
	v_lshlrev_b32_e32 v190, 6, v190
	v_mad_u32_u24 v190, v188, 63, v190
	v_mov_b32_e32 v191, 0xff
	v_mov_b32_e32 v189, 0x1fff
	v_cmp_gt_u32_e32 vcc, 0x8000, v190
	s_nop 1
	v_cndmask_b32_e32 v191, v191, v189, vcc
	v_and_b32_e32 v189, v190, v191
	v_or_b32_e32 v192, v189, v188
	v_cmp_eq_u32_e32 vcc, 0, v192
	s_nop 1
	v_cndmask_b32_e64 v100, v100, 0, vcc
	v_cndmask_b32_e64 v101, v101, 0, vcc
	v_cndmask_b32_e64 v102, v102, 0, vcc
	v_cndmask_b32_e64 v103, v103, 0, vcc
	v_cndmask_b32_e64 v104, v104, 0, vcc
	v_cndmask_b32_e64 v105, v105, 0, vcc
	v_cndmask_b32_e64 v106, v106, 0, vcc
	v_cndmask_b32_e64 v107, v107, 0, vcc
	v_cmp_eq_u32_e64 s[26:27], v189, v191
	v_cmp_eq_u32_e32 vcc, 1, v188
	s_nop 1
	s_and_b64 vcc, vcc, s[26:27]
	s_nop 1
	v_cndmask_b32_e64 v116, v116, 0, vcc
	v_cndmask_b32_e64 v117, v117, 0, vcc
	v_cndmask_b32_e64 v118, v118, 0, vcc
	v_cndmask_b32_e64 v119, v119, 0, vcc
	v_cndmask_b32_e64 v120, v120, 0, vcc
	v_cndmask_b32_e64 v121, v121, 0, vcc
	v_cndmask_b32_e64 v122, v122, 0, vcc
	v_cndmask_b32_e64 v123, v123, 0, vcc
	v_lshlrev_b32_e32 v204, 16, v100
	v_lshlrev_b32_e32 v205, 16, v108
	v_lshlrev_b32_e32 v206, 16, v116
	v_fma_f32 v200, v4, v204, v36
	v_fma_f32 v200, v12, v205, v200
	v_fma_f32 v200, v28, v206, v200
	v_lshlrev_b32_e32 v204, 16, v104
	v_lshlrev_b32_e32 v205, 16, v112
	v_lshlrev_b32_e32 v206, 16, v120
	v_fma_f32 v201, v64, v204, v92
	v_fma_f32 v201, v72, v205, v201
	v_fma_f32 v201, v84, v206, v201
	v_mul_f32_e32 v208, 0xbfb8aa3b, v200
	v_exp_f32_e32 v208, v208
	s_nop 0
	v_add_f32_e32 v209, 1.0, v208
	v_div_scale_f32 v210, s[26:27], v209, v209, v200
	v_rcp_f32_e32 v211, v210
	s_nop 0
	v_fma_f32 v212, -v210, v211, 1.0
	v_fmac_f32_e32 v211, v212, v211
	v_div_scale_f32 v213, vcc, v200, v209, v200
	v_mul_f32_e32 v214, v213, v211
	v_fma_f32 v215, -v210, v214, v213
	v_fmac_f32_e32 v214, v215, v211
	v_fma_f32 v210, -v210, v214, v213
	v_div_fmas_f32 v210, v210, v211, v214
	v_div_fixup_f32 v210, v210, v209, v200
	v_mul_f32_e32 v216, v210, v201
	v_and_b32_e32 v204, 0xffff0000, v100
	v_and_b32_e32 v205, 0xffff0000, v108
	v_and_b32_e32 v206, 0xffff0000, v116
	v_fma_f32 v200, v5, v204, v37
	v_fma_f32 v200, v13, v205, v200
	v_fma_f32 v200, v29, v206, v200
	v_and_b32_e32 v204, 0xffff0000, v104
	v_and_b32_e32 v205, 0xffff0000, v112
	v_and_b32_e32 v206, 0xffff0000, v120
	v_fma_f32 v201, v65, v204, v93
	v_fma_f32 v201, v73, v205, v201
	v_fma_f32 v201, v85, v206, v201
	v_mul_f32_e32 v208, 0xbfb8aa3b, v200
	v_exp_f32_e32 v208, v208
	s_nop 0
	v_add_f32_e32 v209, 1.0, v208
	v_div_scale_f32 v210, s[26:27], v209, v209, v200
	v_rcp_f32_e32 v211, v210
	s_nop 0
	v_fma_f32 v212, -v210, v211, 1.0
	v_fmac_f32_e32 v211, v212, v211
	v_div_scale_f32 v213, vcc, v200, v209, v200
	v_mul_f32_e32 v214, v213, v211
	v_fma_f32 v215, -v210, v214, v213
	v_fmac_f32_e32 v214, v215, v211
	v_fma_f32 v210, -v210, v214, v213
	v_div_fmas_f32 v210, v210, v211, v214
	v_div_fixup_f32 v210, v210, v209, v200
	v_mul_f32_e32 v217, v210, v201
	v_bfe_u32 v220, v216, 16, 1
	v_bfe_u32 v221, v217, 16, 1
	v_add3_u32 v220, v216, v220, s10
	v_add3_u32 v221, v217, v221, s10
	v_lshrrev_b32_e32 v220, 16, v220
	v_and_or_b32 v196, v221, s11, v220
	v_lshlrev_b32_e32 v204, 16, v101
	v_lshlrev_b32_e32 v205, 16, v109
	v_lshlrev_b32_e32 v206, 16, v117
	v_fma_f32 v200, v6, v204, v38
	v_fma_f32 v200, v14, v205, v200
	v_fma_f32 v200, v30, v206, v200
	v_lshlrev_b32_e32 v204, 16, v105
	v_lshlrev_b32_e32 v205, 16, v113
	v_lshlrev_b32_e32 v206, 16, v121
	v_fma_f32 v201, v66, v204, v94
	v_fma_f32 v201, v74, v205, v201
	v_fma_f32 v201, v86, v206, v201
	v_mul_f32_e32 v208, 0xbfb8aa3b, v200
	v_exp_f32_e32 v208, v208
	s_nop 0
	v_add_f32_e32 v209, 1.0, v208
	v_div_scale_f32 v210, s[26:27], v209, v209, v200
	v_rcp_f32_e32 v211, v210
	s_nop 0
	v_fma_f32 v212, -v210, v211, 1.0
	v_fmac_f32_e32 v211, v212, v211
	v_div_scale_f32 v213, vcc, v200, v209, v200
	v_mul_f32_e32 v214, v213, v211
	v_fma_f32 v215, -v210, v214, v213
	v_fmac_f32_e32 v214, v215, v211
	v_fma_f32 v210, -v210, v214, v213
	v_div_fmas_f32 v210, v210, v211, v214
	v_div_fixup_f32 v210, v210, v209, v200
	v_mul_f32_e32 v216, v210, v201
	v_and_b32_e32 v204, 0xffff0000, v101
	v_and_b32_e32 v205, 0xffff0000, v109
	v_and_b32_e32 v206, 0xffff0000, v117
	v_fma_f32 v200, v7, v204, v39
	v_fma_f32 v200, v15, v205, v200
	v_fma_f32 v200, v31, v206, v200
	v_and_b32_e32 v204, 0xffff0000, v105
	v_and_b32_e32 v205, 0xffff0000, v113
	v_and_b32_e32 v206, 0xffff0000, v121
	v_fma_f32 v201, v67, v204, v95
	v_fma_f32 v201, v75, v205, v201
	v_fma_f32 v201, v87, v206, v201
	v_mul_f32_e32 v208, 0xbfb8aa3b, v200
	v_exp_f32_e32 v208, v208
	s_nop 0
	v_add_f32_e32 v209, 1.0, v208
	v_div_scale_f32 v210, s[26:27], v209, v209, v200
	v_rcp_f32_e32 v211, v210
	s_nop 0
	v_fma_f32 v212, -v210, v211, 1.0
	v_fmac_f32_e32 v211, v212, v211
	v_div_scale_f32 v213, vcc, v200, v209, v200
	v_mul_f32_e32 v214, v213, v211
	v_fma_f32 v215, -v210, v214, v213
	v_fmac_f32_e32 v214, v215, v211
	v_fma_f32 v210, -v210, v214, v213
	v_div_fmas_f32 v210, v210, v211, v214
	v_div_fixup_f32 v210, v210, v209, v200
	v_mul_f32_e32 v217, v210, v201
	v_bfe_u32 v220, v216, 16, 1
	v_bfe_u32 v221, v217, 16, 1
	v_add3_u32 v220, v216, v220, s10
	v_add3_u32 v221, v217, v221, s10
	v_lshrrev_b32_e32 v220, 16, v220
	v_and_or_b32 v197, v221, s11, v220
	v_lshlrev_b32_e32 v204, 16, v102
	v_lshlrev_b32_e32 v205, 16, v110
	v_lshlrev_b32_e32 v206, 16, v118
	v_fma_f32 v200, v8, v204, v40
	v_fma_f32 v200, v24, v205, v200
	v_fma_f32 v200, v32, v206, v200
	v_lshlrev_b32_e32 v204, 16, v106
	v_lshlrev_b32_e32 v205, 16, v114
	v_lshlrev_b32_e32 v206, 16, v122
; DI unsigned pk2(float lo, float hi) { return f2bf(lo) | (f2bf(hi) << 16); }
; DI float silu_f(float x) { return x / (1.f + __expf(-x)); }
; DI void ffn_fixup_phase(const Args& A, int wave_s, int l, int rows) {
;     ...
;             for (int hlf = 0; hlf < 2; ++hlf) {
;                 const int i = c8 + 2 * q + hlf;
;                 const float ua0 = hlf ? __builtin_bit_cast(float, a0[q] & 0xffff0000u) : __builtin_bit_cast(float, a0[q] << 16);
;                 const float ua1 = hlf ? __builtin_bit_cast(float, a1[q] & 0xffff0000u) : __builtin_bit_cast(float, a1[q] << 16);
;                 const float ua2 = hlf ? __builtin_bit_cast(float, a2[q] & 0xffff0000u) : __builtin_bit_cast(float, a2[q] << 16);
;                 const float ub0 = hlf ? __builtin_bit_cast(float, b0[q] & 0xffff0000u) : __builtin_bit_cast(float, b0[q] << 16);
;                 const float ub1 = hlf ? __builtin_bit_cast(float, b1[q] & 0xffff0000u) : __builtin_bit_cast(float, b1[q] << 16);
;                 const float ub2 = hlf ? __builtin_bit_cast(float, b2[q] & 0xffff0000u) : __builtin_bit_cast(float, b2[q] << 16);
;                 const float ya = cb[i] + ua0 * cw[i] + ua1 * cw[5632 + i] + ua2 * cw[2 * 5632 + i];
;                 const float yv = cb[2816 + i] + ub0 * cw[2816 + i] + ub1 * cw[5632 + 2816 + i] + ub2 * cw[2 * 5632 + 2816 + i];
;                 r2[hlf] = silu_f(ya) * yv;
;             }
;             res[q] = pk2(r2[0], r2[1]);
;         }
;         v4u o; o.x = res[0]; o.y = res[1]; o.z = res[2]; o.w = res[3];
;         *(v4u*)(ACTF + (size_t)R * 2816 + c8) = o;
	v_fma_f32 v201, v68, v204, v96
	v_fma_f32 v201, v80, v205, v201
	v_fma_f32 v201, v88, v206, v201
	v_mul_f32_e32 v208, 0xbfb8aa3b, v200
	v_exp_f32_e32 v208, v208
	s_nop 0
	v_add_f32_e32 v209, 1.0, v208
	v_div_scale_f32 v210, s[26:27], v209, v209, v200
	v_rcp_f32_e32 v211, v210
	s_nop 0
	v_fma_f32 v212, -v210, v211, 1.0
	v_fmac_f32_e32 v211, v212, v211
	v_div_scale_f32 v213, vcc, v200, v209, v200
	v_mul_f32_e32 v214, v213, v211
	v_fma_f32 v215, -v210, v214, v213
	v_fmac_f32_e32 v214, v215, v211
	v_fma_f32 v210, -v210, v214, v213
	v_div_fmas_f32 v210, v210, v211, v214
	v_div_fixup_f32 v210, v210, v209, v200
	v_mul_f32_e32 v216, v210, v201
	v_and_b32_e32 v204, 0xffff0000, v102
	v_and_b32_e32 v205, 0xffff0000, v110
	v_and_b32_e32 v206, 0xffff0000, v118
	v_fma_f32 v200, v9, v204, v41
	v_fma_f32 v200, v25, v205, v200
	v_fma_f32 v200, v33, v206, v200
	v_and_b32_e32 v204, 0xffff0000, v106
	v_and_b32_e32 v205, 0xffff0000, v114
	v_and_b32_e32 v206, 0xffff0000, v122
	v_fma_f32 v201, v69, v204, v97
	v_fma_f32 v201, v81, v205, v201
	v_fma_f32 v201, v89, v206, v201
	v_mul_f32_e32 v208, 0xbfb8aa3b, v200
	v_exp_f32_e32 v208, v208
	s_nop 0
	v_add_f32_e32 v209, 1.0, v208
	v_div_scale_f32 v210, s[26:27], v209, v209, v200
	v_rcp_f32_e32 v211, v210
	s_nop 0
	v_fma_f32 v212, -v210, v211, 1.0
	v_fmac_f32_e32 v211, v212, v211
	v_div_scale_f32 v213, vcc, v200, v209, v200
	v_mul_f32_e32 v214, v213, v211
	v_fma_f32 v215, -v210, v214, v213
	v_fmac_f32_e32 v214, v215, v211
	v_fma_f32 v210, -v210, v214, v213
	v_div_fmas_f32 v210, v210, v211, v214
	v_div_fixup_f32 v210, v210, v209, v200
	v_mul_f32_e32 v217, v210, v201
	v_bfe_u32 v220, v216, 16, 1
	v_bfe_u32 v221, v217, 16, 1
	v_add3_u32 v220, v216, v220, s10
	v_add3_u32 v221, v217, v221, s10
	v_lshrrev_b32_e32 v220, 16, v220
	v_and_or_b32 v198, v221, s11, v220
	v_lshlrev_b32_e32 v204, 16, v103
	v_lshlrev_b32_e32 v205, 16, v111
	v_lshlrev_b32_e32 v206, 16, v119
	v_fma_f32 v200, v10, v204, v42
	v_fma_f32 v200, v26, v205, v200
	v_fma_f32 v200, v34, v206, v200
	v_lshlrev_b32_e32 v204, 16, v107
	v_lshlrev_b32_e32 v205, 16, v115
	v_lshlrev_b32_e32 v206, 16, v123
	v_fma_f32 v201, v70, v204, v98
	v_fma_f32 v201, v82, v205, v201
	v_fma_f32 v201, v90, v206, v201
	v_mul_f32_e32 v208, 0xbfb8aa3b, v200
	v_exp_f32_e32 v208, v208
	s_nop 0
	v_add_f32_e32 v209, 1.0, v208
	v_div_scale_f32 v210, s[26:27], v209, v209, v200
	v_rcp_f32_e32 v211, v210
	s_nop 0
	v_fma_f32 v212, -v210, v211, 1.0
	v_fmac_f32_e32 v211, v212, v211
	v_div_scale_f32 v213, vcc, v200, v209, v200
	v_mul_f32_e32 v214, v213, v211
	v_fma_f32 v215, -v210, v214, v213
	v_fmac_f32_e32 v214, v215, v211
	v_fma_f32 v210, -v210, v214, v213
	v_div_fmas_f32 v210, v210, v211, v214
	v_div_fixup_f32 v210, v210, v209, v200
	v_mul_f32_e32 v216, v210, v201
	v_and_b32_e32 v204, 0xffff0000, v103
	v_and_b32_e32 v205, 0xffff0000, v111
	v_and_b32_e32 v206, 0xffff0000, v119
	v_fma_f32 v200, v11, v204, v43
	v_fma_f32 v200, v27, v205, v200
	v_fma_f32 v200, v35, v206, v200
	v_and_b32_e32 v204, 0xffff0000, v107
	v_and_b32_e32 v205, 0xffff0000, v115
	v_and_b32_e32 v206, 0xffff0000, v123
	v_fma_f32 v201, v71, v204, v99
	v_fma_f32 v201, v83, v205, v201
	v_fma_f32 v201, v91, v206, v201
	v_mul_f32_e32 v208, 0xbfb8aa3b, v200
	v_exp_f32_e32 v208, v208
	s_nop 0
	v_add_f32_e32 v209, 1.0, v208
	v_div_scale_f32 v210, s[26:27], v209, v209, v200
	v_rcp_f32_e32 v211, v210
	s_nop 0
	v_fma_f32 v212, -v210, v211, 1.0
	v_fmac_f32_e32 v211, v212, v211
	v_div_scale_f32 v213, vcc, v200, v209, v200
	v_mul_f32_e32 v214, v213, v211
	v_fma_f32 v215, -v210, v214, v213
	v_fmac_f32_e32 v214, v215, v211
	v_fma_f32 v210, -v210, v214, v213
	v_div_fmas_f32 v210, v210, v211, v214
	v_div_fixup_f32 v210, v210, v209, v200
	v_mul_f32_e32 v217, v210, v201
	v_bfe_u32 v220, v216, 16, 1
	v_bfe_u32 v221, v217, 16, 1
	v_add3_u32 v220, v216, v220, s10
	v_add3_u32 v221, v217, v221, s10
	v_lshrrev_b32_e32 v220, 16, v220
	v_and_or_b32 v199, v221, s11, v220
	v_mov_b32_e32 v192, v224
	v_cmp_gt_u32_e32 vcc, s7, v192
	v_mov_b32_e32 v193, 0x1600
	v_mul_lo_u32 v193, v190, v193
	v_add_u32_e32 v180, v193, v227
	v_mov_b32_e32 v181, 0
	v_lshl_add_u64 v[180:181], v[180:181], 0, s[30:31]
	s_and_saveexec_b64 s[26:27], vcc
	global_store_dwordx4 v[180:181], v[196:199], off
	s_mov_b64 exec, s[26:27]
	s_nop 1
	s_waitcnt vmcnt(7)
; DI float silu_f(float x) { return x / (1.f + __expf(-x)); }
; DI void ffn_fixup_phase(const Args& A, int wave_s, int l, int rows) {
;     ...
;         const int R = kb * 64 + (side ? 63 : 0);
;         bool first, last;
;         if (R < NLAT) { first = (R & 8191) == 0; last = (R & 8191) == 8191; } else { first = ((R - NLAT) & 255) == 0; last = ((R - NLAT) & 255) == 255; }
;         const v4u z = {0u, 0u, 0u, 0u};
;         const bf16* pp = side ? UB + (size_t)((kb * 4 + 2) * 2) * 2816 : UB + (size_t)(((kb - 1) * 4 + 3) * 2) * 2816;
;         const bf16* pc = UB + (size_t)((kb * 4 + (side ? 3 : 0)) * 2) * 2816;
;         const bf16* pn = side ? UB + (size_t)(((kb + 1) * 4 + 0) * 2) * 2816 : UB + (size_t)((kb * 4 + 1) * 2) * 2816;
;         const bool zp = (!side) && first, zn = side && last;
;         const v4u a0 = zp ? z : *(const v4u*)(pp + c8), a1 = *(const v4u*)(pc + c8), a2 = zn ? z : *(const v4u*)(pn + c8);
;         const v4u b0 = zp ? z : *(const v4u*)(pp + 2816 + c8), b1 = *(const v4u*)(pc + 2816 + c8), b2 = zn ? z : *(const v4u*)(pn + 2816 + c8);
;         unsigned res[4];
; #pragma unroll
;         for (int q = 0; q < 4; ++q) {
;             float r2[2];
; #pragma unroll
;             for (int hlf = 0; hlf < 2; ++hlf) {
;                 const int i = c8 + 2 * q + hlf;
;                 const float ua0 = hlf ? __builtin_bit_cast(float, a0[q] & 0xffff0000u) : __builtin_bit_cast(float, a0[q] << 16);
;                 const float ua1 = hlf ? __builtin_bit_cast(float, a1[q] & 0xffff0000u) : __builtin_bit_cast(float, a1[q] << 16);
;                 const float ua2 = hlf ? __builtin_bit_cast(float, a2[q] & 0xffff0000u) : __builtin_bit_cast(float, a2[q] << 16);
;                 const float ub0 = hlf ? __builtin_bit_cast(float, b0[q] & 0xffff0000u) : __builtin_bit_cast(float, b0[q] << 16);
;                 const float ub1 = hlf ? __builtin_bit_cast(float, b1[q] & 0xffff0000u) : __builtin_bit_cast(float, b1[q] << 16);
;                 const float ub2 = hlf ? __builtin_bit_cast(float, b2[q] & 0xffff0000u) : __builtin_bit_cast(float, b2[q] << 16);
;                 const float ya = cb[i] + ua0 * cw[i] + ua1 * cw[5632 + i] + ua2 * cw[2 * 5632 + i];
;                 const float yv = cb[2816 + i] + ub0 * cw[2816 + i] + ub1 * cw[5632 + 2816 + i] + ub2 * cw[2 * 5632 + 2816 + i];
;                 r2[hlf] = silu_f(ya) * yv;
	v_and_b32_e32 v188, 1, v230
	v_lshrrev_b32_e32 v190, 1, v230
	v_lshlrev_b32_e32 v190, 6, v190
	v_mad_u32_u24 v190, v188, 63, v190
	v_mov_b32_e32 v191, 0xff
	v_mov_b32_e32 v189, 0x1fff
	v_cmp_gt_u32_e32 vcc, 0x8000, v190
	s_nop 1
	v_cndmask_b32_e32 v191, v191, v189, vcc
	v_and_b32_e32 v189, v190, v191
	v_or_b32_e32 v192, v189, v188
	v_cmp_eq_u32_e32 vcc, 0, v192
	s_nop 1
	v_cndmask_b32_e64 v124, v124, 0, vcc
	v_cndmask_b32_e64 v125, v125, 0, vcc
	v_cndmask_b32_e64 v126, v126, 0, vcc
	v_cndmask_b32_e64 v127, v127, 0, vcc
	v_cndmask_b32_e64 v128, v128, 0, vcc
	v_cndmask_b32_e64 v129, v129, 0, vcc
	v_cndmask_b32_e64 v130, v130, 0, vcc
	v_cndmask_b32_e64 v131, v131, 0, vcc
	v_cmp_eq_u32_e64 s[26:27], v189, v191
	v_cmp_eq_u32_e32 vcc, 1, v188
	s_nop 1
	s_and_b64 vcc, vcc, s[26:27]
	s_nop 1
	v_cndmask_b32_e64 v140, v140, 0, vcc
	v_cndmask_b32_e64 v141, v141, 0, vcc
	v_cndmask_b32_e64 v142, v142, 0, vcc
	v_cndmask_b32_e64 v143, v143, 0, vcc
	v_cndmask_b32_e64 v144, v144, 0, vcc
	v_cndmask_b32_e64 v145, v145, 0, vcc
	v_cndmask_b32_e64 v146, v146, 0, vcc
	v_cndmask_b32_e64 v147, v147, 0, vcc
	v_lshlrev_b32_e32 v204, 16, v124
	v_lshlrev_b32_e32 v205, 16, v132
	v_lshlrev_b32_e32 v206, 16, v140
	v_fma_f32 v200, v4, v204, v36
	v_fma_f32 v200, v12, v205, v200
	v_fma_f32 v200, v28, v206, v200
	v_lshlrev_b32_e32 v204, 16, v128
	v_lshlrev_b32_e32 v205, 16, v136
	v_lshlrev_b32_e32 v206, 16, v144
	v_fma_f32 v201, v64, v204, v92
	v_fma_f32 v201, v72, v205, v201
	v_fma_f32 v201, v84, v206, v201
	v_mul_f32_e32 v208, 0xbfb8aa3b, v200
	v_exp_f32_e32 v208, v208
	s_nop 0
	v_add_f32_e32 v209, 1.0, v208
	v_div_scale_f32 v210, s[26:27], v209, v209, v200
	v_rcp_f32_e32 v211, v210
	s_nop 0
	v_fma_f32 v212, -v210, v211, 1.0
	v_fmac_f32_e32 v211, v212, v211
	v_div_scale_f32 v213, vcc, v200, v209, v200
	v_mul_f32_e32 v214, v213, v211
	v_fma_f32 v215, -v210, v214, v213
	v_fmac_f32_e32 v214, v215, v211
	v_fma_f32 v210, -v210, v214, v213
	v_div_fmas_f32 v210, v210, v211, v214
	v_div_fixup_f32 v210, v210, v209, v200
	v_mul_f32_e32 v216, v210, v201
	v_and_b32_e32 v204, 0xffff0000, v124
	v_and_b32_e32 v205, 0xffff0000, v132
	v_and_b32_e32 v206, 0xffff0000, v140
	v_fma_f32 v200, v5, v204, v37
	v_fma_f32 v200, v13, v205, v200
	v_fma_f32 v200, v29, v206, v200
	v_and_b32_e32 v204, 0xffff0000, v128
	v_and_b32_e32 v205, 0xffff0000, v136
	v_and_b32_e32 v206, 0xffff0000, v144
	v_fma_f32 v201, v65, v204, v93
	v_fma_f32 v201, v73, v205, v201
	v_fma_f32 v201, v85, v206, v201
	v_mul_f32_e32 v208, 0xbfb8aa3b, v200
	v_exp_f32_e32 v208, v208
	s_nop 0
	v_add_f32_e32 v209, 1.0, v208
	v_div_scale_f32 v210, s[26:27], v209, v209, v200
	v_rcp_f32_e32 v211, v210
	s_nop 0
	v_fma_f32 v212, -v210, v211, 1.0
	v_fmac_f32_e32 v211, v212, v211
	v_div_scale_f32 v213, vcc, v200, v209, v200
	v_mul_f32_e32 v214, v213, v211
	v_fma_f32 v215, -v210, v214, v213
	v_fmac_f32_e32 v214, v215, v211
	v_fma_f32 v210, -v210, v214, v213
	v_div_fmas_f32 v210, v210, v211, v214
	v_div_fixup_f32 v210, v210, v209, v200
	v_mul_f32_e32 v217, v210, v201
	v_bfe_u32 v220, v216, 16, 1
	v_bfe_u32 v221, v217, 16, 1
	v_add3_u32 v220, v216, v220, s10
	v_add3_u32 v221, v217, v221, s10
	v_lshrrev_b32_e32 v220, 16, v220
	v_and_or_b32 v196, v221, s11, v220
	v_lshlrev_b32_e32 v204, 16, v125
	v_lshlrev_b32_e32 v205, 16, v133
	v_lshlrev_b32_e32 v206, 16, v141
	v_fma_f32 v200, v6, v204, v38
	v_fma_f32 v200, v14, v205, v200
	v_fma_f32 v200, v30, v206, v200
	v_lshlrev_b32_e32 v204, 16, v129
	v_lshlrev_b32_e32 v205, 16, v137
	v_lshlrev_b32_e32 v206, 16, v145
	v_fma_f32 v201, v66, v204, v94
	v_fma_f32 v201, v74, v205, v201
	v_fma_f32 v201, v86, v206, v201
	v_mul_f32_e32 v208, 0xbfb8aa3b, v200
	v_exp_f32_e32 v208, v208
	s_nop 0
	v_add_f32_e32 v209, 1.0, v208
	v_div_scale_f32 v210, s[26:27], v209, v209, v200
	v_rcp_f32_e32 v211, v210
	s_nop 0
	v_fma_f32 v212, -v210, v211, 1.0
	v_fmac_f32_e32 v211, v212, v211
	v_div_scale_f32 v213, vcc, v200, v209, v200
	v_mul_f32_e32 v214, v213, v211
	v_fma_f32 v215, -v210, v214, v213
	v_fmac_f32_e32 v214, v215, v211
	v_fma_f32 v210, -v210, v214, v213
	v_div_fmas_f32 v210, v210, v211, v214
	v_div_fixup_f32 v210, v210, v209, v200
	v_mul_f32_e32 v216, v210, v201
	v_and_b32_e32 v204, 0xffff0000, v125
	v_and_b32_e32 v205, 0xffff0000, v133
	v_and_b32_e32 v206, 0xffff0000, v141
	v_fma_f32 v200, v7, v204, v39
	v_fma_f32 v200, v15, v205, v200
	v_fma_f32 v200, v31, v206, v200
	v_and_b32_e32 v204, 0xffff0000, v129
	v_and_b32_e32 v205, 0xffff0000, v137
	v_and_b32_e32 v206, 0xffff0000, v145
	v_fma_f32 v201, v67, v204, v95
	v_fma_f32 v201, v75, v205, v201
	v_fma_f32 v201, v87, v206, v201
	v_mul_f32_e32 v208, 0xbfb8aa3b, v200
	v_exp_f32_e32 v208, v208
	s_nop 0
	v_add_f32_e32 v209, 1.0, v208
	v_div_scale_f32 v210, s[26:27], v209, v209, v200
	v_rcp_f32_e32 v211, v210
	s_nop 0
	v_fma_f32 v212, -v210, v211, 1.0
	v_fmac_f32_e32 v211, v212, v211
	v_div_scale_f32 v213, vcc, v200, v209, v200
	v_mul_f32_e32 v214, v213, v211
	v_fma_f32 v215, -v210, v214, v213
	v_fmac_f32_e32 v214, v215, v211
	v_fma_f32 v210, -v210, v214, v213
	v_div_fmas_f32 v210, v210, v211, v214
	v_div_fixup_f32 v210, v210, v209, v200
	v_mul_f32_e32 v217, v210, v201
	v_bfe_u32 v220, v216, 16, 1
	v_bfe_u32 v221, v217, 16, 1
	v_add3_u32 v220, v216, v220, s10
	v_add3_u32 v221, v217, v221, s10
	v_lshrrev_b32_e32 v220, 16, v220
	v_and_or_b32 v197, v221, s11, v220
	v_lshlrev_b32_e32 v204, 16, v126
	v_lshlrev_b32_e32 v205, 16, v134
	v_lshlrev_b32_e32 v206, 16, v142
	v_fma_f32 v200, v8, v204, v40
	v_fma_f32 v200, v24, v205, v200
	v_fma_f32 v200, v32, v206, v200
	v_lshlrev_b32_e32 v204, 16, v130
	v_lshlrev_b32_e32 v205, 16, v138
	v_lshlrev_b32_e32 v206, 16, v146
; DI unsigned pk2(float lo, float hi) { return f2bf(lo) | (f2bf(hi) << 16); }
; DI float silu_f(float x) { return x / (1.f + __expf(-x)); }
; DI void ffn_fixup_phase(const Args& A, int wave_s, int l, int rows) {
;     ...
;             for (int hlf = 0; hlf < 2; ++hlf) {
;                 const int i = c8 + 2 * q + hlf;
;                 const float ua0 = hlf ? __builtin_bit_cast(float, a0[q] & 0xffff0000u) : __builtin_bit_cast(float, a0[q] << 16);
;                 const float ua1 = hlf ? __builtin_bit_cast(float, a1[q] & 0xffff0000u) : __builtin_bit_cast(float, a1[q] << 16);
;                 const float ua2 = hlf ? __builtin_bit_cast(float, a2[q] & 0xffff0000u) : __builtin_bit_cast(float, a2[q] << 16);
;                 const float ub0 = hlf ? __builtin_bit_cast(float, b0[q] & 0xffff0000u) : __builtin_bit_cast(float, b0[q] << 16);
;                 const float ub1 = hlf ? __builtin_bit_cast(float, b1[q] & 0xffff0000u) : __builtin_bit_cast(float, b1[q] << 16);
;                 const float ub2 = hlf ? __builtin_bit_cast(float, b2[q] & 0xffff0000u) : __builtin_bit_cast(float, b2[q] << 16);
;                 const float ya = cb[i] + ua0 * cw[i] + ua1 * cw[5632 + i] + ua2 * cw[2 * 5632 + i];
;                 const float yv = cb[2816 + i] + ub0 * cw[2816 + i] + ub1 * cw[5632 + 2816 + i] + ub2 * cw[2 * 5632 + 2816 + i];
;                 r2[hlf] = silu_f(ya) * yv;
;             }
;             res[q] = pk2(r2[0], r2[1]);
;         }
;         v4u o; o.x = res[0]; o.y = res[1]; o.z = res[2]; o.w = res[3];
;         *(v4u*)(ACTF + (size_t)R * 2816 + c8) = o;
	v_fma_f32 v201, v68, v204, v96
	v_fma_f32 v201, v80, v205, v201
	v_fma_f32 v201, v88, v206, v201
	v_mul_f32_e32 v208, 0xbfb8aa3b, v200
	v_exp_f32_e32 v208, v208
	s_nop 0
	v_add_f32_e32 v209, 1.0, v208
	v_div_scale_f32 v210, s[26:27], v209, v209, v200
	v_rcp_f32_e32 v211, v210
	s_nop 0
	v_fma_f32 v212, -v210, v211, 1.0
	v_fmac_f32_e32 v211, v212, v211
	v_div_scale_f32 v213, vcc, v200, v209, v200
	v_mul_f32_e32 v214, v213, v211
	v_fma_f32 v215, -v210, v214, v213
	v_fmac_f32_e32 v214, v215, v211
	v_fma_f32 v210, -v210, v214, v213
	v_div_fmas_f32 v210, v210, v211, v214
	v_div_fixup_f32 v210, v210, v209, v200
	v_mul_f32_e32 v216, v210, v201
	v_and_b32_e32 v204, 0xffff0000, v126
	v_and_b32_e32 v205, 0xffff0000, v134
	v_and_b32_e32 v206, 0xffff0000, v142
	v_fma_f32 v200, v9, v204, v41
	v_fma_f32 v200, v25, v205, v200
	v_fma_f32 v200, v33, v206, v200
	v_and_b32_e32 v204, 0xffff0000, v130
	v_and_b32_e32 v205, 0xffff0000, v138
	v_and_b32_e32 v206, 0xffff0000, v146
	v_fma_f32 v201, v69, v204, v97
	v_fma_f32 v201, v81, v205, v201
	v_fma_f32 v201, v89, v206, v201
	v_mul_f32_e32 v208, 0xbfb8aa3b, v200
	v_exp_f32_e32 v208, v208
	s_nop 0
	v_add_f32_e32 v209, 1.0, v208
	v_div_scale_f32 v210, s[26:27], v209, v209, v200
	v_rcp_f32_e32 v211, v210
	s_nop 0
	v_fma_f32 v212, -v210, v211, 1.0
	v_fmac_f32_e32 v211, v212, v211
	v_div_scale_f32 v213, vcc, v200, v209, v200
	v_mul_f32_e32 v214, v213, v211
	v_fma_f32 v215, -v210, v214, v213
	v_fmac_f32_e32 v214, v215, v211
	v_fma_f32 v210, -v210, v214, v213
	v_div_fmas_f32 v210, v210, v211, v214
	v_div_fixup_f32 v210, v210, v209, v200
	v_mul_f32_e32 v217, v210, v201
	v_bfe_u32 v220, v216, 16, 1
	v_bfe_u32 v221, v217, 16, 1
	v_add3_u32 v220, v216, v220, s10
	v_add3_u32 v221, v217, v221, s10
	v_lshrrev_b32_e32 v220, 16, v220
	v_and_or_b32 v198, v221, s11, v220
	v_lshlrev_b32_e32 v204, 16, v127
	v_lshlrev_b32_e32 v205, 16, v135
	v_lshlrev_b32_e32 v206, 16, v143
	v_fma_f32 v200, v10, v204, v42
	v_fma_f32 v200, v26, v205, v200
	v_fma_f32 v200, v34, v206, v200
	v_lshlrev_b32_e32 v204, 16, v131
	v_lshlrev_b32_e32 v205, 16, v139
	v_lshlrev_b32_e32 v206, 16, v147
	v_fma_f32 v201, v70, v204, v98
	v_fma_f32 v201, v82, v205, v201
	v_fma_f32 v201, v90, v206, v201
	v_mul_f32_e32 v208, 0xbfb8aa3b, v200
	v_exp_f32_e32 v208, v208
	s_nop 0
	v_add_f32_e32 v209, 1.0, v208
	v_div_scale_f32 v210, s[26:27], v209, v209, v200
	v_rcp_f32_e32 v211, v210
	s_nop 0
	v_fma_f32 v212, -v210, v211, 1.0
	v_fmac_f32_e32 v211, v212, v211
	v_div_scale_f32 v213, vcc, v200, v209, v200
	v_mul_f32_e32 v214, v213, v211
	v_fma_f32 v215, -v210, v214, v213
	v_fmac_f32_e32 v214, v215, v211
	v_fma_f32 v210, -v210, v214, v213
	v_div_fmas_f32 v210, v210, v211, v214
	v_div_fixup_f32 v210, v210, v209, v200
	v_mul_f32_e32 v216, v210, v201
	v_and_b32_e32 v204, 0xffff0000, v127
	v_and_b32_e32 v205, 0xffff0000, v135
	v_and_b32_e32 v206, 0xffff0000, v143
	v_fma_f32 v200, v11, v204, v43
	v_fma_f32 v200, v27, v205, v200
	v_fma_f32 v200, v35, v206, v200
	v_and_b32_e32 v204, 0xffff0000, v131
	v_and_b32_e32 v205, 0xffff0000, v139
	v_and_b32_e32 v206, 0xffff0000, v147
	v_fma_f32 v201, v71, v204, v99
	v_fma_f32 v201, v83, v205, v201
	v_fma_f32 v201, v91, v206, v201
	v_mul_f32_e32 v208, 0xbfb8aa3b, v200
	v_exp_f32_e32 v208, v208
	s_nop 0
	v_add_f32_e32 v209, 1.0, v208
	v_div_scale_f32 v210, s[26:27], v209, v209, v200
	v_rcp_f32_e32 v211, v210
	s_nop 0
	v_fma_f32 v212, -v210, v211, 1.0
	v_fmac_f32_e32 v211, v212, v211
	v_div_scale_f32 v213, vcc, v200, v209, v200
	v_mul_f32_e32 v214, v213, v211
	v_fma_f32 v215, -v210, v214, v213
	v_fmac_f32_e32 v214, v215, v211
	v_fma_f32 v210, -v210, v214, v213
	v_div_fmas_f32 v210, v210, v211, v214
	v_div_fixup_f32 v210, v210, v209, v200
	v_mul_f32_e32 v217, v210, v201
	v_bfe_u32 v220, v216, 16, 1
	v_bfe_u32 v221, v217, 16, 1
	v_add3_u32 v220, v216, v220, s10
	v_add3_u32 v221, v217, v221, s10
	v_lshrrev_b32_e32 v220, 16, v220
	v_and_or_b32 v199, v221, s11, v220
	v_add_u32_e32 v192, 130944, v224
	v_cmp_gt_u32_e32 vcc, s7, v192
	v_mov_b32_e32 v193, 0x1600
	v_mul_lo_u32 v193, v190, v193
	v_add_u32_e32 v180, v193, v227
	v_mov_b32_e32 v181, 0
	v_lshl_add_u64 v[180:181], v[180:181], 0, s[30:31]
	s_and_saveexec_b64 s[26:27], vcc
	global_store_dwordx4 v[180:181], v[196:199], off
	s_mov_b64 exec, s[26:27]
	s_nop 1
	s_waitcnt vmcnt(2)
; DI void ffn_fixup_phase(const Args& A, int wave_s, int l, int rows) {
;     ...
;         const int c8 = (e % 352) * 8, rs = e / 352, side = rs & 1, kb = rs >> 1;
;         const int R = kb * 64 + (side ? 63 : 0);
;         bool first, last;
;         if (R < NLAT) { first = (R & 8191) == 0; last = (R & 8191) == 8191; } else { first = ((R - NLAT) & 255) == 0; last = ((R - NLAT) & 255) == 255; }
;         const v4u z = {0u, 0u, 0u, 0u};
;         const bf16* pp = side ? UB + (size_t)((kb * 4 + 2) * 2) * 2816 : UB + (size_t)(((kb - 1) * 4 + 3) * 2) * 2816;
;         const bf16* pc = UB + (size_t)((kb * 4 + (side ? 3 : 0)) * 2) * 2816;
;         const bf16* pn = side ? UB + (size_t)(((kb + 1) * 4 + 0) * 2) * 2816 : UB + (size_t)((kb * 4 + 1) * 2) * 2816;
;         const bool zp = (!side) && first, zn = side && last;
;         const v4u a0 = zp ? z : *(const v4u*)(pp + c8), a1 = *(const v4u*)(pc + c8), a2 = zn ? z : *(const v4u*)(pn + c8);
;         const v4u b0 = zp ? z : *(const v4u*)(pp + 2816 + c8), b1 = *(const v4u*)(pc + 2816 + c8), b2 = zn ? z : *(const v4u*)(pn + 2816 + c8);
;         unsigned res[4];
; #pragma unroll
;         for (int q = 0; q < 4; ++q) {
;             float r2[2];
; #pragma unroll
;             for (int hlf = 0; hlf < 2; ++hlf) {
;                 const int i = c8 + 2 * q + hlf;
;                 const float ua0 = hlf ? __builtin_bit_cast(float, a0[q] & 0xffff0000u) : __builtin_bit_cast(float, a0[q] << 16);
;                 const float ua1 = hlf ? __builtin_bit_cast(float, a1[q] & 0xffff0000u) : __builtin_bit_cast(float, a1[q] << 16);
;                 const float ua2 = hlf ? __builtin_bit_cast(float, a2[q] & 0xffff0000u) : __builtin_bit_cast(float, a2[q] << 16);
;                 const float ub0 = hlf ? __builtin_bit_cast(float, b0[q] & 0xffff0000u) : __builtin_bit_cast(float, b0[q] << 16);
;                 const float ub1 = hlf ? __builtin_bit_cast(float, b1[q] & 0xffff0000u) : __builtin_bit_cast(float, b1[q] << 16);
;                 const float ub2 = hlf ? __builtin_bit_cast(float, b2[q] & 0xffff0000u) : __builtin_bit_cast(float, b2[q] << 16);
;                 const float ya = cb[i] + ua0 * cw[i] + ua1 * cw[5632 + i] + ua2 * cw[2 * 5632 + i];
;                 const float yv = cb[2816 + i] + ub0 * cw[2816 + i] + ub1 * cw[5632 + 2816 + i] + ub2 * cw[2 * 5632 + 2816 + i];
;                 r2[hlf] = silu_f(ya) * yv;
;             }
	v_and_b32_e32 v188, 1, v231
	v_lshrrev_b32_e32 v190, 1, v231
	v_lshlrev_b32_e32 v190, 6, v190
	v_mad_u32_u24 v190, v188, 63, v190
	v_mov_b32_e32 v191, 0xff
	v_mov_b32_e32 v189, 0x1fff
	v_cmp_gt_u32_e32 vcc, 0x8000, v190
	s_nop 1
	v_cndmask_b32_e32 v191, v191, v189, vcc
	v_and_b32_e32 v189, v190, v191
	v_or_b32_e32 v192, v189, v188
	v_cmp_eq_u32_e32 vcc, 0, v192
	s_nop 1
	v_cndmask_b32_e64 v148, v148, 0, vcc
	v_cndmask_b32_e64 v149, v149, 0, vcc
	v_cndmask_b32_e64 v150, v150, 0, vcc
	v_cndmask_b32_e64 v151, v151, 0, vcc
	v_cndmask_b32_e64 v152, v152, 0, vcc
	v_cndmask_b32_e64 v153, v153, 0, vcc
	v_cndmask_b32_e64 v154, v154, 0, vcc
	v_cndmask_b32_e64 v155, v155, 0, vcc
	v_cmp_eq_u32_e64 s[26:27], v189, v191
	v_cmp_eq_u32_e32 vcc, 1, v188
	s_nop 1
	s_and_b64 vcc, vcc, s[26:27]
	s_nop 1
	v_cndmask_b32_e64 v168, v168, 0, vcc
	v_cndmask_b32_e64 v169, v169, 0, vcc
	v_cndmask_b32_e64 v170, v170, 0, vcc
	v_cndmask_b32_e64 v171, v171, 0, vcc
	v_cndmask_b32_e64 v172, v172, 0, vcc
	v_cndmask_b32_e64 v173, v173, 0, vcc
	v_cndmask_b32_e64 v174, v174, 0, vcc
	v_cndmask_b32_e64 v175, v175, 0, vcc
	v_lshlrev_b32_e32 v204, 16, v148
	v_lshlrev_b32_e32 v205, 16, v156
	v_lshlrev_b32_e32 v206, 16, v168
	v_fma_f32 v200, v4, v204, v36
	v_fma_f32 v200, v12, v205, v200
	v_fma_f32 v200, v28, v206, v200
	v_lshlrev_b32_e32 v204, 16, v152
	v_lshlrev_b32_e32 v205, 16, v164
	v_lshlrev_b32_e32 v206, 16, v172
	v_fma_f32 v201, v64, v204, v92
	v_fma_f32 v201, v72, v205, v201
	v_fma_f32 v201, v84, v206, v201
	v_mul_f32_e32 v208, 0xbfb8aa3b, v200
	v_exp_f32_e32 v208, v208
	s_nop 0
	v_add_f32_e32 v209, 1.0, v208
	v_div_scale_f32 v210, s[26:27], v209, v209, v200
	v_rcp_f32_e32 v211, v210
	s_nop 0
	v_fma_f32 v212, -v210, v211, 1.0
	v_fmac_f32_e32 v211, v212, v211
	v_div_scale_f32 v213, vcc, v200, v209, v200
	v_mul_f32_e32 v214, v213, v211
	v_fma_f32 v215, -v210, v214, v213
	v_fmac_f32_e32 v214, v215, v211
	v_fma_f32 v210, -v210, v214, v213
	v_div_fmas_f32 v210, v210, v211, v214
	v_div_fixup_f32 v210, v210, v209, v200
	v_mul_f32_e32 v216, v210, v201
	v_and_b32_e32 v204, 0xffff0000, v148
	v_and_b32_e32 v205, 0xffff0000, v156
	v_and_b32_e32 v206, 0xffff0000, v168
	v_fma_f32 v200, v5, v204, v37
	v_fma_f32 v200, v13, v205, v200
	v_fma_f32 v200, v29, v206, v200
	v_and_b32_e32 v204, 0xffff0000, v152
	v_and_b32_e32 v205, 0xffff0000, v164
	v_and_b32_e32 v206, 0xffff0000, v172
	v_fma_f32 v201, v65, v204, v93
	v_fma_f32 v201, v73, v205, v201
	v_fma_f32 v201, v85, v206, v201
	v_mul_f32_e32 v208, 0xbfb8aa3b, v200
	v_exp_f32_e32 v208, v208
	s_nop 0
	v_add_f32_e32 v209, 1.0, v208
	v_div_scale_f32 v210, s[26:27], v209, v209, v200
	v_rcp_f32_e32 v211, v210
	s_nop 0
	v_fma_f32 v212, -v210, v211, 1.0
	v_fmac_f32_e32 v211, v212, v211
	v_div_scale_f32 v213, vcc, v200, v209, v200
	v_mul_f32_e32 v214, v213, v211
	v_fma_f32 v215, -v210, v214, v213
	v_fmac_f32_e32 v214, v215, v211
	v_fma_f32 v210, -v210, v214, v213
	v_div_fmas_f32 v210, v210, v211, v214
	v_div_fixup_f32 v210, v210, v209, v200
	v_mul_f32_e32 v217, v210, v201
	v_bfe_u32 v220, v216, 16, 1
	v_bfe_u32 v221, v217, 16, 1
	v_add3_u32 v220, v216, v220, s10
	v_add3_u32 v221, v217, v221, s10
	v_lshrrev_b32_e32 v220, 16, v220
	v_and_or_b32 v196, v221, s11, v220
	v_lshlrev_b32_e32 v204, 16, v149
	v_lshlrev_b32_e32 v205, 16, v157
	v_lshlrev_b32_e32 v206, 16, v169
	v_fma_f32 v200, v6, v204, v38
	v_fma_f32 v200, v14, v205, v200
	v_fma_f32 v200, v30, v206, v200
	v_lshlrev_b32_e32 v204, 16, v153
	v_lshlrev_b32_e32 v205, 16, v165
	v_lshlrev_b32_e32 v206, 16, v173
	v_fma_f32 v201, v66, v204, v94
	v_fma_f32 v201, v74, v205, v201
	v_fma_f32 v201, v86, v206, v201
	v_mul_f32_e32 v208, 0xbfb8aa3b, v200
	v_exp_f32_e32 v208, v208
	s_nop 0
	v_add_f32_e32 v209, 1.0, v208
	v_div_scale_f32 v210, s[26:27], v209, v209, v200
	v_rcp_f32_e32 v211, v210
	s_nop 0
	v_fma_f32 v212, -v210, v211, 1.0
	v_fmac_f32_e32 v211, v212, v211
	v_div_scale_f32 v213, vcc, v200, v209, v200
	v_mul_f32_e32 v214, v213, v211
	v_fma_f32 v215, -v210, v214, v213
	v_fmac_f32_e32 v214, v215, v211
	v_fma_f32 v210, -v210, v214, v213
	v_div_fmas_f32 v210, v210, v211, v214
	v_div_fixup_f32 v210, v210, v209, v200
	v_mul_f32_e32 v216, v210, v201
	v_and_b32_e32 v204, 0xffff0000, v149
	v_and_b32_e32 v205, 0xffff0000, v157
	v_and_b32_e32 v206, 0xffff0000, v169
	v_fma_f32 v200, v7, v204, v39
	v_fma_f32 v200, v15, v205, v200
	v_fma_f32 v200, v31, v206, v200
	v_and_b32_e32 v204, 0xffff0000, v153
	v_and_b32_e32 v205, 0xffff0000, v165
	v_and_b32_e32 v206, 0xffff0000, v173
	v_fma_f32 v201, v67, v204, v95
	v_fma_f32 v201, v75, v205, v201
	v_fma_f32 v201, v87, v206, v201
	v_mul_f32_e32 v208, 0xbfb8aa3b, v200
	v_exp_f32_e32 v208, v208
	s_nop 0
	v_add_f32_e32 v209, 1.0, v208
	v_div_scale_f32 v210, s[26:27], v209, v209, v200
	v_rcp_f32_e32 v211, v210
	s_nop 0
	v_fma_f32 v212, -v210, v211, 1.0
	v_fmac_f32_e32 v211, v212, v211
	v_div_scale_f32 v213, vcc, v200, v209, v200
	v_mul_f32_e32 v214, v213, v211
	v_fma_f32 v215, -v210, v214, v213
; DI unsigned pk2(float lo, float hi) { return f2bf(lo) | (f2bf(hi) << 16); }
; DI float silu_f(float x) { return x / (1.f + __expf(-x)); }
; DI void ffn_fixup_phase(const Args& A, int wave_s, int l, int rows) {
;     ...
;             for (int hlf = 0; hlf < 2; ++hlf) {
;                 const int i = c8 + 2 * q + hlf;
;                 const float ua0 = hlf ? __builtin_bit_cast(float, a0[q] & 0xffff0000u) : __builtin_bit_cast(float, a0[q] << 16);
;                 const float ua1 = hlf ? __builtin_bit_cast(float, a1[q] & 0xffff0000u) : __builtin_bit_cast(float, a1[q] << 16);
;                 const float ua2 = hlf ? __builtin_bit_cast(float, a2[q] & 0xffff0000u) : __builtin_bit_cast(float, a2[q] << 16);
;                 const float ub0 = hlf ? __builtin_bit_cast(float, b0[q] & 0xffff0000u) : __builtin_bit_cast(float, b0[q] << 16);
;                 const float ub1 = hlf ? __builtin_bit_cast(float, b1[q] & 0xffff0000u) : __builtin_bit_cast(float, b1[q] << 16);
;                 const float ub2 = hlf ? __builtin_bit_cast(float, b2[q] & 0xffff0000u) : __builtin_bit_cast(float, b2[q] << 16);
;                 const float ya = cb[i] + ua0 * cw[i] + ua1 * cw[5632 + i] + ua2 * cw[2 * 5632 + i];
;                 const float yv = cb[2816 + i] + ub0 * cw[2816 + i] + ub1 * cw[5632 + 2816 + i] + ub2 * cw[2 * 5632 + 2816 + i];
;                 r2[hlf] = silu_f(ya) * yv;
;             }
;             res[q] = pk2(r2[0], r2[1]);
;         }
;         v4u o; o.x = res[0]; o.y = res[1]; o.z = res[2]; o.w = res[3];
;         *(v4u*)(ACTF + (size_t)R * 2816 + c8) = o;
	v_fmac_f32_e32 v214, v215, v211
	v_fma_f32 v210, -v210, v214, v213
	v_div_fmas_f32 v210, v210, v211, v214
	v_div_fixup_f32 v210, v210, v209, v200
	v_mul_f32_e32 v217, v210, v201
	v_bfe_u32 v220, v216, 16, 1
	v_bfe_u32 v221, v217, 16, 1
	v_add3_u32 v220, v216, v220, s10
	v_add3_u32 v221, v217, v221, s10
	v_lshrrev_b32_e32 v220, 16, v220
	v_and_or_b32 v197, v221, s11, v220
	v_lshlrev_b32_e32 v204, 16, v150
	v_lshlrev_b32_e32 v205, 16, v158
	v_lshlrev_b32_e32 v206, 16, v170
	v_fma_f32 v200, v8, v204, v40
	v_fma_f32 v200, v24, v205, v200
	v_fma_f32 v200, v32, v206, v200
	v_lshlrev_b32_e32 v204, 16, v154
	v_lshlrev_b32_e32 v205, 16, v166
	v_lshlrev_b32_e32 v206, 16, v174
	v_fma_f32 v201, v68, v204, v96
	v_fma_f32 v201, v80, v205, v201
	v_fma_f32 v201, v88, v206, v201
	v_mul_f32_e32 v208, 0xbfb8aa3b, v200
	v_exp_f32_e32 v208, v208
	s_nop 0
	v_add_f32_e32 v209, 1.0, v208
	v_div_scale_f32 v210, s[26:27], v209, v209, v200
	v_rcp_f32_e32 v211, v210
	s_nop 0
	v_fma_f32 v212, -v210, v211, 1.0
	v_fmac_f32_e32 v211, v212, v211
	v_div_scale_f32 v213, vcc, v200, v209, v200
	v_mul_f32_e32 v214, v213, v211
	v_fma_f32 v215, -v210, v214, v213
	v_fmac_f32_e32 v214, v215, v211
	v_fma_f32 v210, -v210, v214, v213
	v_div_fmas_f32 v210, v210, v211, v214
	v_div_fixup_f32 v210, v210, v209, v200
	v_mul_f32_e32 v216, v210, v201
	v_and_b32_e32 v204, 0xffff0000, v150
	v_and_b32_e32 v205, 0xffff0000, v158
	v_and_b32_e32 v206, 0xffff0000, v170
	v_fma_f32 v200, v9, v204, v41
	v_fma_f32 v200, v25, v205, v200
	v_fma_f32 v200, v33, v206, v200
	v_and_b32_e32 v204, 0xffff0000, v154
	v_and_b32_e32 v205, 0xffff0000, v166
	v_and_b32_e32 v206, 0xffff0000, v174
	v_fma_f32 v201, v69, v204, v97
	v_fma_f32 v201, v81, v205, v201
	v_fma_f32 v201, v89, v206, v201
	v_mul_f32_e32 v208, 0xbfb8aa3b, v200
	v_exp_f32_e32 v208, v208
	s_nop 0
	v_add_f32_e32 v209, 1.0, v208
	v_div_scale_f32 v210, s[26:27], v209, v209, v200
	v_rcp_f32_e32 v211, v210
	s_nop 0
	v_fma_f32 v212, -v210, v211, 1.0
	v_fmac_f32_e32 v211, v212, v211
	v_div_scale_f32 v213, vcc, v200, v209, v200
	v_mul_f32_e32 v214, v213, v211
	v_fma_f32 v215, -v210, v214, v213
	v_fmac_f32_e32 v214, v215, v211
	v_fma_f32 v210, -v210, v214, v213
	v_div_fmas_f32 v210, v210, v211, v214
	v_div_fixup_f32 v210, v210, v209, v200
	v_mul_f32_e32 v217, v210, v201
	v_bfe_u32 v220, v216, 16, 1
	v_bfe_u32 v221, v217, 16, 1
	v_add3_u32 v220, v216, v220, s10
	v_add3_u32 v221, v217, v221, s10
	v_lshrrev_b32_e32 v220, 16, v220
	v_and_or_b32 v198, v221, s11, v220
	v_lshlrev_b32_e32 v204, 16, v151
	v_lshlrev_b32_e32 v205, 16, v159
	v_lshlrev_b32_e32 v206, 16, v171
	v_fma_f32 v200, v10, v204, v42
	v_fma_f32 v200, v26, v205, v200
	v_fma_f32 v200, v34, v206, v200
	v_lshlrev_b32_e32 v204, 16, v155
	v_lshlrev_b32_e32 v205, 16, v167
	v_lshlrev_b32_e32 v206, 16, v175
	v_fma_f32 v201, v70, v204, v98
	v_fma_f32 v201, v82, v205, v201
	v_fma_f32 v201, v90, v206, v201
	v_mul_f32_e32 v208, 0xbfb8aa3b, v200
	v_exp_f32_e32 v208, v208
	s_nop 0
	v_add_f32_e32 v209, 1.0, v208
	v_div_scale_f32 v210, s[26:27], v209, v209, v200
	v_rcp_f32_e32 v211, v210
	s_nop 0
	v_fma_f32 v212, -v210, v211, 1.0
	v_fmac_f32_e32 v211, v212, v211
	v_div_scale_f32 v213, vcc, v200, v209, v200
	v_mul_f32_e32 v214, v213, v211
	v_fma_f32 v215, -v210, v214, v213
	v_fmac_f32_e32 v214, v215, v211
	v_fma_f32 v210, -v210, v214, v213
	v_div_fmas_f32 v210, v210, v211, v214
	v_div_fixup_f32 v210, v210, v209, v200
	v_mul_f32_e32 v216, v210, v201
	v_and_b32_e32 v204, 0xffff0000, v151
	v_and_b32_e32 v205, 0xffff0000, v159
	v_and_b32_e32 v206, 0xffff0000, v171
	v_fma_f32 v200, v11, v204, v43
	v_fma_f32 v200, v27, v205, v200
	v_fma_f32 v200, v35, v206, v200
	v_and_b32_e32 v204, 0xffff0000, v155
	v_and_b32_e32 v205, 0xffff0000, v167
	v_and_b32_e32 v206, 0xffff0000, v175
	v_fma_f32 v201, v71, v204, v99
	v_fma_f32 v201, v83, v205, v201
	v_fma_f32 v201, v91, v206, v201
	v_mul_f32_e32 v208, 0xbfb8aa3b, v200
	v_exp_f32_e32 v208, v208
	s_nop 0
	v_add_f32_e32 v209, 1.0, v208
	v_div_scale_f32 v210, s[26:27], v209, v209, v200
	v_rcp_f32_e32 v211, v210
	s_nop 0
	v_fma_f32 v212, -v210, v211, 1.0
	v_fmac_f32_e32 v211, v212, v211
	v_div_scale_f32 v213, vcc, v200, v209, v200
	v_mul_f32_e32 v214, v213, v211
	v_fma_f32 v215, -v210, v214, v213
	v_fmac_f32_e32 v214, v215, v211
	v_fma_f32 v210, -v210, v214, v213
	v_div_fmas_f32 v210, v210, v211, v214
	v_div_fixup_f32 v210, v210, v209, v200
	v_mul_f32_e32 v217, v210, v201
	v_bfe_u32 v220, v216, 16, 1
	v_bfe_u32 v221, v217, 16, 1
	v_add3_u32 v220, v216, v220, s10
	v_add3_u32 v221, v217, v221, s10
	v_lshrrev_b32_e32 v220, 16, v220
	v_and_or_b32 v199, v221, s11, v220
	v_add_u32_e32 v192, 261888, v224
	v_cmp_gt_u32_e32 vcc, s7, v192
	v_mov_b32_e32 v193, 0x1600
	v_mul_lo_u32 v193, v190, v193
	v_add_u32_e32 v180, v193, v227
	v_mov_b32_e32 v181, 0
	v_lshl_add_u64 v[180:181], v[180:181], 0, s[30:31]
	s_and_saveexec_b64 s[26:27], vcc
	global_store_dwordx4 v[180:181], v[196:199], off
	s_mov_b64 exec, s[26:27]
	s_nop 1

;     __device__ __forceinline__ void operator()(const f32x4 (&acc)[2][2][4][2], const Unit& u, int wr, int wc, int fr, int fq) const {
;         const bool isctx = u.pm >= 128;
;         const int v = isctx ? 4 : (u.pm >> 5);
;         const float* bp = isctx ? base_ctx - (size_t)32768 * 1024 : base_lat;
;         float* op = isctx ? out_ctx - (size_t)32768 * 1024 : out_lat;
;         const float* g = gate + v * 6144;
;         const int row0 = u.pm * BM + wr * 64 + fr; const int col0 = u.pn * BM + wc * 32 + 4 * fq;
;         f32x4 gv[2][2];
; #pragma unroll
;         for (int bj = 0; bj < 2; ++bj)
; #pragma unroll
;             for (int n = 0; n < 2; ++n) gv[bj][n] = *(const f32x4*)(g + col0 + bj * HALF + n * 16);
; #pragma unroll
;         for (int ai = 0; ai < 2; ++ai) {
;             f32x4 bs[4][2][2];
; #pragma unroll
;             for (int m = 0; m < 4; ++m) { const size_t off = (size_t)(row0 + ai * HALF + m * 16) * 1024 + col0;
; #pragma unroll
;                 for (int bj = 0; bj < 2; ++bj)
; #pragma unroll
;                     for (int n = 0; n < 2; ++n) bs[m][bj][n] = *(const f32x4*)(bp + off + bj * HALF + n * 16); }
; #pragma unroll
;             for (int m = 0; m < 4; ++m) { const size_t off = (size_t)(row0 + ai * HALF + m * 16) * 1024 + col0;
; #pragma unroll
;                 for (int bj = 0; bj < 2; ++bj)
; #pragma unroll
;                     for (int n = 0; n < 2; ++n) *(f32x4*)(op + off + bj * HALF + n * 16) = bs[m][bj][n] + gv[bj][n] * acc[ai][bj][m][n]; }
.LBB0_775:
	s_lshr_b32 s16, s40, 5
	v_readlane_b32 s44, v252, 17
	s_cmpk_gt_i32 s40, 0x7f
	s_mulk_i32 s16, 0x1800
	v_readlane_b32 s58, v252, 31
	v_readlane_b32 s17, v254, 12
	s_cselect_b32 s16, 0x6000, s16
	v_readlane_b32 s59, v252, 32
	s_cselect_b32 s18, s17, s58
	v_readlane_b32 s17, v254, 13
	s_cselect_b32 s19, s17, s59
	s_ashr_i32 s17, s16, 31
	s_lshl_b64 s[16:17], s[16:17], 2
	v_lshl_or_b32 v128, s41, 8, v154
	s_add_u32 s16, s33, s16
	v_ashrrev_i32_e32 v129, 31, v128
	v_lshl_add_u32 v164, s40, 8, v152
	s_addc_u32 s17, s34, s17
	v_lshlrev_b64 v[150:151], 2, v[128:129]
	v_ashrrev_i32_e32 v165, 31, v164
	v_lshl_add_u64 v[128:129], s[16:17], 0, v[150:151]
	v_lshl_add_u64 v[166:167], s[18:19], 0, v[150:151]
	v_lshlrev_b64 v[150:151], 12, v[164:165]
	v_or_b32_e32 v180, 16, v164
	v_or_b32_e32 v196, 32, v164
	v_or_b32_e32 v164, 48, v164
	v_ashrrev_i32_e32 v181, 31, v180
	v_ashrrev_i32_e32 v197, 31, v196
	v_ashrrev_i32_e32 v165, 31, v164
	v_lshlrev_b64 v[180:181], 12, v[180:181]
	v_lshlrev_b64 v[196:197], 12, v[196:197]
	v_lshlrev_b64 v[164:165], 12, v[164:165]
	v_lshl_add_u64 v[150:151], v[166:167], 0, v[150:151]
	v_lshl_add_u64 v[228:229], v[166:167], 0, v[180:181]
	v_lshl_add_u64 v[230:231], v[166:167], 0, v[196:197]
	v_lshl_add_u64 v[164:165], v[166:167], 0, v[164:165]
	global_load_dwordx4 v[140:143], v[128:129], off
	global_load_dwordx4 v[136:139], v[128:129], off offset:64
	global_load_dwordx4 v[132:135], v[128:129], off offset:512
	s_nop 0
	global_load_dwordx4 v[128:131], v[128:129], off offset:576
	s_nop 0
	global_load_dwordx4 v[156:159], v[150:151], off nt
	global_load_dwordx4 v[168:171], v[150:151], off offset:64 nt
	global_load_dwordx4 v[172:175], v[150:151], off offset:512 nt
	global_load_dwordx4 v[176:179], v[150:151], off offset:576 nt
	global_load_dwordx4 v[180:183], v[228:229], off nt
	global_load_dwordx4 v[184:187], v[228:229], off offset:64 nt
	global_load_dwordx4 v[188:191], v[228:229], off offset:512 nt
	global_load_dwordx4 v[192:195], v[228:229], off offset:576 nt
	global_load_dwordx4 v[196:199], v[230:231], off nt
	global_load_dwordx4 v[200:203], v[230:231], off offset:64 nt
	global_load_dwordx4 v[204:207], v[230:231], off offset:512 nt
	global_load_dwordx4 v[208:211], v[230:231], off offset:576 nt
	global_load_dwordx4 v[212:215], v[164:165], off nt
	global_load_dwordx4 v[216:219], v[164:165], off offset:64 nt
	global_load_dwordx4 v[220:223], v[164:165], off offset:512 nt
	global_load_dwordx4 v[224:227], v[164:165], off offset:576 nt
	s_mov_b64 s[16:17], 0x80000
	v_readlane_b32 s45, v252, 18
	v_readlane_b32 s46, v252, 19
	v_readlane_b32 s47, v252, 20
	v_readlane_b32 s48, v252, 21
	v_readlane_b32 s49, v252, 22
	v_readlane_b32 s50, v252, 23
	v_readlane_b32 s51, v252, 24
	v_readlane_b32 s52, v252, 25
	v_readlane_b32 s53, v252, 26
	v_readlane_b32 s54, v252, 27
	v_readlane_b32 s55, v252, 28
	v_readlane_b32 s56, v252, 29
	v_readlane_b32 s57, v252, 30
	s_waitcnt vmcnt(0)
	v_pk_fma_f32 v[124:125], v[124:125], v[140:141], v[156:157]
	v_lshl_add_u64 v[156:157], v[150:151], 0, s[16:17]
	s_mov_b32 s16, 0x80000
	v_pk_fma_f32 v[126:127], v[126:127], v[142:143], v[158:159]
	v_pk_fma_f32 v[74:75], v[74:75], v[138:139], v[218:219]
	v_pk_fma_f32 v[72:73], v[72:73], v[136:137], v[216:217]
	v_pk_fma_f32 v[70:71], v[70:71], v[134:135], v[222:223]
	v_pk_fma_f32 v[68:69], v[68:69], v[132:133], v[220:221]
	v_pk_fma_f32 v[66:67], v[66:67], v[130:131], v[226:227]
	v_pk_fma_f32 v[64:65], v[64:65], v[128:129], v[224:225]
	v_add_co_u32_e32 v158, vcc, s16, v150
	s_mov_b64 s[16:17], 0x90000
	v_pk_fma_f32 v[122:123], v[122:123], v[138:139], v[170:171]
	v_pk_fma_f32 v[120:121], v[120:121], v[136:137], v[168:169]
	v_pk_fma_f32 v[114:115], v[114:115], v[134:135], v[174:175]
	v_pk_fma_f32 v[112:113], v[112:113], v[132:133], v[172:173]
	v_pk_fma_f32 v[106:107], v[106:107], v[130:131], v[178:179]
	v_pk_fma_f32 v[104:105], v[104:105], v[128:129], v[176:177]
	v_pk_fma_f32 v[118:119], v[118:119], v[142:143], v[182:183]
	v_pk_fma_f32 v[116:117], v[116:117], v[140:141], v[180:181]
	v_pk_fma_f32 v[110:111], v[110:111], v[138:139], v[186:187]
	v_pk_fma_f32 v[108:109], v[108:109], v[136:137], v[184:185]
	v_pk_fma_f32 v[98:99], v[98:99], v[134:135], v[190:191]
	v_pk_fma_f32 v[96:97], v[96:97], v[132:133], v[188:189]
	v_pk_fma_f32 v[90:91], v[90:91], v[130:131], v[194:195]
	v_pk_fma_f32 v[88:89], v[88:89], v[128:129], v[192:193]
	v_pk_fma_f32 v[102:103], v[102:103], v[142:143], v[198:199]
	v_pk_fma_f32 v[100:101], v[100:101], v[140:141], v[196:197]
	v_pk_fma_f32 v[94:95], v[94:95], v[138:139], v[202:203]
	v_pk_fma_f32 v[92:93], v[92:93], v[136:137], v[200:201]
	v_pk_fma_f32 v[82:83], v[82:83], v[134:135], v[206:207]
	v_pk_fma_f32 v[80:81], v[80:81], v[132:133], v[204:205]
	v_pk_fma_f32 v[78:79], v[78:79], v[130:131], v[210:211]
	v_pk_fma_f32 v[76:77], v[76:77], v[128:129], v[208:209]
	v_pk_fma_f32 v[86:87], v[86:87], v[142:143], v[214:215]
	v_pk_fma_f32 v[84:85], v[84:85], v[140:141], v[212:213]
	global_store_dwordx4 v[150:151], v[124:127], off
	global_store_dwordx4 v[150:151], v[120:123], off offset:64
	global_store_dwordx4 v[150:151], v[112:115], off offset:512
	global_store_dwordx4 v[150:151], v[104:107], off offset:576
; #define PG8_BAR __builtin_amdgcn_s_barrier()
;     __device__ __forceinline__ void operator()(const f32x4 (&acc)[2][2][4][2], const Unit& u, int wr, int wc, int fr, int fq) const {
;     ...
;             for (int m = 0; m < 4; ++m) { const size_t off = (size_t)(row0 + ai * HALF + m * 16) * 1024 + col0;
; #pragma unroll
;                 for (int bj = 0; bj < 2; ++bj)
; #pragma unroll
;                     for (int n = 0; n < 2; ++n) bs[m][bj][n] = *(const f32x4*)(bp + off + bj * HALF + n * 16); }
; #pragma unroll
;             for (int m = 0; m < 4; ++m) { const size_t off = (size_t)(row0 + ai * HALF + m * 16) * 1024 + col0;
; #pragma unroll
;                 for (int bj = 0; bj < 2; ++bj)
; #pragma unroll
;                     for (int n = 0; n < 2; ++n) *(f32x4*)(op + off + bj * HALF + n * 16) = bs[m][bj][n] + gv[bj][n] * acc[ai][bj][m][n]; }
; template <class Epi, class Sched, bool ALIGN_EPI = false, bool SP2 = false>
; __device__ __forceinline__ void gemm_phase(PG8_LAS unsigned char* lds, const Gemm g, const Sched& S, const Epi& E, int tid_in) {
;     ...
;         if (!has_next) break;
; #pragma unroll
;         for (int a = 0; a < 2; ++a)
; #pragma unroll
;             for (int b = 0; b < 2; ++b)
; #pragma unroll
;                 for (int m = 0; m < 4; ++m)
; #pragma unroll
;                     for (int n = 0; n < 2; ++n) acc[a][b][m][n] = (f32x4){0.f, 0.f, 0.f, 0.f};
;         cur = nxt; cA = nA; cB = nB; ++ui;
;         if constexpr (ALIGN_EPI) { if (wr == 1) PG8_BAR; }
;     }
	global_store_dwordx4 v[228:229], v[116:119], off
	global_store_dwordx4 v[228:229], v[108:111], off offset:64
	global_store_dwordx4 v[228:229], v[96:99], off offset:512
	global_store_dwordx4 v[228:229], v[88:91], off offset:576
	global_store_dwordx4 v[230:231], v[100:103], off
	global_store_dwordx4 v[230:231], v[92:95], off offset:64
	global_store_dwordx4 v[230:231], v[80:83], off offset:512
	global_store_dwordx4 v[230:231], v[76:79], off offset:576
	global_store_dwordx4 v[164:165], v[84:87], off
	global_store_dwordx4 v[164:165], v[72:75], off offset:64
	global_store_dwordx4 v[164:165], v[68:71], off offset:512
	global_store_dwordx4 v[164:165], v[64:67], off offset:576
	v_addc_co_u32_e32 v159, vcc, 0, v151, vcc
	v_lshl_add_u64 v[164:165], v[150:151], 0, s[16:17]
	s_mov_b32 s16, 0x90000
	v_add_co_u32_e32 v166, vcc, s16, v150
	s_mov_b64 s[16:17], 0xa0000
	s_nop 0
	v_addc_co_u32_e32 v167, vcc, 0, v151, vcc
	v_lshl_add_u64 v[168:169], v[150:151], 0, s[16:17]
	s_mov_b32 s16, 0xa0000
	v_add_co_u32_e32 v170, vcc, s16, v150
	s_mov_b32 s16, 0xb0000
	s_nop 0
	v_addc_co_u32_e32 v171, vcc, 0, v151, vcc
	v_add_co_u32_e32 v172, vcc, s16, v150
	s_mov_b64 s[16:17], 0xb0000
	s_nop 0
	v_addc_co_u32_e32 v173, vcc, 0, v151, vcc
	v_lshl_add_u64 v[150:151], v[150:151], 0, s[16:17]
	global_load_dwordx4 v[64:67], v[156:157], off offset:64 nt
	global_load_dwordx4 v[68:71], v[156:157], off offset:512 nt
	global_load_dwordx4 v[72:75], v[158:159], off nt
	global_load_dwordx4 v[76:79], v[156:157], off offset:576 nt
	global_load_dwordx4 v[80:83], v[166:167], off nt
	global_load_dwordx4 v[84:87], v[164:165], off offset:64 nt
	global_load_dwordx4 v[88:91], v[164:165], off offset:512 nt
	global_load_dwordx4 v[92:95], v[164:165], off offset:576 nt
	global_load_dwordx4 v[96:99], v[170:171], off nt
	global_load_dwordx4 v[100:103], v[168:169], off offset:64 nt
	global_load_dwordx4 v[104:107], v[168:169], off offset:512 nt
	global_load_dwordx4 v[108:111], v[168:169], off offset:576 nt
	global_load_dwordx4 v[112:115], v[172:173], off nt
	global_load_dwordx4 v[116:119], v[150:151], off offset:64 nt
	global_load_dwordx4 v[120:123], v[150:151], off offset:512 nt
	global_load_dwordx4 v[124:127], v[150:151], off offset:576 nt
	s_and_b64 vcc, exec, s[6:7]
	s_mov_b64 s[6:7], -1
	s_waitcnt vmcnt(15)
	v_pk_fma_f32 v[58:59], v[58:59], v[138:139], v[66:67]
	v_pk_fma_f32 v[56:57], v[56:57], v[136:137], v[64:65]
	s_waitcnt vmcnt(13)
	v_pk_fma_f32 v[62:63], v[62:63], v[142:143], v[74:75]
	v_pk_fma_f32 v[60:61], v[60:61], v[140:141], v[72:73]
	v_pk_fma_f32 v[50:51], v[50:51], v[134:135], v[70:71]
	s_waitcnt vmcnt(2)
	v_pk_fma_f32 v[10:11], v[10:11], v[138:139], v[118:119]
	v_pk_fma_f32 v[18:19], v[18:19], v[142:143], v[114:115]
	v_pk_fma_f32 v[16:17], v[16:17], v[140:141], v[112:113]
	v_pk_fma_f32 v[8:9], v[8:9], v[136:137], v[116:117]
	s_waitcnt vmcnt(1)
	v_pk_fma_f32 v[6:7], v[6:7], v[134:135], v[122:123]
	v_pk_fma_f32 v[4:5], v[4:5], v[132:133], v[120:121]
	s_waitcnt vmcnt(0)
	v_pk_fma_f32 v[2:3], v[2:3], v[130:131], v[126:127]
	v_pk_fma_f32 v[0:1], v[0:1], v[128:129], v[124:125]
	v_pk_fma_f32 v[48:49], v[48:49], v[132:133], v[68:69]
	v_pk_fma_f32 v[42:43], v[42:43], v[130:131], v[78:79]
	v_pk_fma_f32 v[40:41], v[40:41], v[128:129], v[76:77]
	v_pk_fma_f32 v[54:55], v[54:55], v[142:143], v[82:83]
	v_pk_fma_f32 v[52:53], v[52:53], v[140:141], v[80:81]
	v_pk_fma_f32 v[46:47], v[46:47], v[138:139], v[86:87]
	v_pk_fma_f32 v[44:45], v[44:45], v[136:137], v[84:85]
	v_pk_fma_f32 v[34:35], v[34:35], v[134:135], v[90:91]
	v_pk_fma_f32 v[32:33], v[32:33], v[132:133], v[88:89]
	v_pk_fma_f32 v[26:27], v[26:27], v[130:131], v[94:95]
	v_pk_fma_f32 v[24:25], v[24:25], v[128:129], v[92:93]
	v_pk_fma_f32 v[38:39], v[38:39], v[142:143], v[98:99]
	v_pk_fma_f32 v[36:37], v[36:37], v[140:141], v[96:97]
	v_pk_fma_f32 v[30:31], v[30:31], v[138:139], v[102:103]
	v_pk_fma_f32 v[28:29], v[28:29], v[136:137], v[100:101]
	v_pk_fma_f32 v[22:23], v[22:23], v[134:135], v[106:107]
	v_pk_fma_f32 v[20:21], v[20:21], v[132:133], v[104:105]
	v_pk_fma_f32 v[14:15], v[14:15], v[130:131], v[110:111]
	v_pk_fma_f32 v[12:13], v[12:13], v[128:129], v[108:109]
	global_store_dwordx4 v[158:159], v[60:63], off
	global_store_dwordx4 v[156:157], v[56:59], off offset:64
	global_store_dwordx4 v[156:157], v[48:51], off offset:512
	global_store_dwordx4 v[156:157], v[40:43], off offset:576
	global_store_dwordx4 v[166:167], v[52:55], off
	global_store_dwordx4 v[164:165], v[44:47], off offset:64
	global_store_dwordx4 v[164:165], v[32:35], off offset:512
	global_store_dwordx4 v[164:165], v[24:27], off offset:576
	global_store_dwordx4 v[170:171], v[36:39], off
	global_store_dwordx4 v[168:169], v[28:31], off offset:64
	global_store_dwordx4 v[168:169], v[20:23], off offset:512
	global_store_dwordx4 v[168:169], v[12:15], off offset:576
	global_store_dwordx4 v[172:173], v[16:19], off
	global_store_dwordx4 v[150:151], v[8:11], off offset:64
	global_store_dwordx4 v[150:151], v[4:7], off offset:512
	global_store_dwordx4 v[150:151], v[0:3], off offset:576
	s_cbranch_vccnz .LBB0_764
	s_andn2_b64 vcc, exec, s[8:9]
	s_cbranch_vccnz .LBB0_763
	s_barrier
	s_branch .LBB0_763
